# g4_tile rewritten by hand: continuous 2-stage LDS-DMA pipeline over 20 K-steps per branch n (16 gate + 4 branch), swizzled LDS, double-buffered fragments, same sigmoid IEEE-div sequence and bf16 RNE r
# speedup vs baseline: 1.0961x; 1.0407x over previous
.LBB0_874:
	s_andn2_b64 vcc, exec, s[2:3]
	s_cbranch_vccnz .LBB0_871
	v_readlane_b32 s20, v255, 4
	v_readlane_b32 s21, v255, 30
	v_and_b32_e32 v144, 63, v216
	v_lshrrev_b32_e32 v145, 6, v216
	v_lshrrev_b32_e32 v146, 3, v144
	v_and_b32_e32 v147, 7, v144
	v_readfirstlane_b32 s12, v145
	v_lshrrev_b32_e32 v148, 1, v146
	v_lshrrev_b32_e32 v149, 2, v146
	v_xor_b32_e32 v150, v148, v149
	v_xor_b32_e32 v151, 5, v150
	v_xor_b32_e32 v150, v147, v150
	v_xor_b32_e32 v151, v147, v151
	v_lshlrev_b32_e32 v150, 4, v150
	v_lshlrev_b32_e32 v151, 4, v151
	v_lshl_add_u32 v152, v145, 5, v146
	v_lshlrev_b32_e32 v153, 11, v152
	v_add_u32_e32 v192, v153, v150
	v_add_u32_e32 v193, v153, v151
	v_add_u32_e32 v193, 0x4000, v193
	v_add_u32_e32 v194, 0x8000, v192
	v_add_u32_e32 v195, 0x8000, v193
	v_lshl_add_u32 v152, v145, 4, v146
	v_lshlrev_b32_e32 v153, 11, v152
	v_add_u32_e32 v196, v153, v150
	v_add_u32_e32 v197, v153, v151
	v_add_u32_e32 v197, 0x4000, v197
	v_lshlrev_b32_e32 v153, 9, v152
	v_add_u32_e32 v198, v153, v150
	v_add_u32_e32 v199, v153, v151
	v_add_u32_e32 v199, 0x1000, v199
	v_and_b32_e32 v154, 15, v144
	v_lshrrev_b32_e32 v155, 4, v144
	v_lshrrev_b32_e32 v156, 1, v154
	v_lshrrev_b32_e32 v157, 2, v154
	v_lshrrev_b32_e32 v158, 3, v154
	v_xor_b32_e32 v157, v157, v158
	v_and_b32_e32 v157, 1, v157
	v_xor_b32_e32 v156, v156, v157
	v_xor_b32_e32 v156, v155, v156
	v_lshlrev_b32_e32 v156, 4, v156
	v_lshl_add_u32 v156, v154, 7, v156
	v_lshrrev_b32_e32 v157, 1, v145
	v_and_b32_e32 v158, 1, v145
	v_lshl_add_u32 v203, v157, 13, v156
	v_xor_b32_e32 v204, 64, v203
	v_lshl_add_u32 v205, v158, 12, v156
	v_xor_b32_e32 v206, 64, v205
	s_lshl_b32 s13, s12, 11
	s_lshl_b32 s12, s12, 12
	s_mov_b32 s30, 0xffff0000
	v_readlane_b32 s2, v253, 4
	v_readlane_b32 s3, v253, 5
	s_lshl_b32 s14, s20, 18
	s_add_u32 s2, s2, s14
	s_addc_u32 s3, s3, 0
	s_add_u32 s8, s50, 0xe629000
	s_addc_u32 s9, s51, 0
	s_add_u32 s8, s8, s14
	s_addc_u32 s9, s9, 0
	s_lshl_b32 s14, s21, 17
	s_add_u32 s4, s50, 0x5990000
	s_addc_u32 s5, s51, 0
	s_add_u32 s4, s4, s14
	s_addc_u32 s5, s5, 0
	s_lshl_b32 s14, s21, 15
	s_add_u32 s10, s50, 0x6190000
	s_addc_u32 s11, s51, 0
	s_add_u32 s10, s10, s14
	s_addc_u32 s11, s11, 0
	s_add_u32 m0, s12, 0x0
	s_nop 0
	global_load_lds_dwordx4 v192, s[2:3]
	s_add_u32 m0, s12, 0x400
	s_nop 0
	global_load_lds_dwordx4 v193, s[2:3]
	s_add_u32 m0, s12, 0x800
	s_nop 0
	global_load_lds_dwordx4 v194, s[2:3]
	s_add_u32 m0, s12, 0xc00
	s_nop 0
	global_load_lds_dwordx4 v195, s[2:3]
	s_add_u32 m0, s13, 0x4000
	s_nop 0
	global_load_lds_dwordx4 v196, s[4:5]
	s_add_u32 m0, s13, 0x4400
	s_nop 0
	global_load_lds_dwordx4 v197, s[4:5]
	s_add_u32 s2, s2, 0x80
	s_addc_u32 s3, s3, 0
	s_add_u32 s4, s4, 0x80
	s_addc_u32 s5, s5, 0
	v_mov_b32_e32 v0, 0
	v_mov_b32_e32 v1, 0
	v_mov_b32_e32 v2, 0
	v_mov_b32_e32 v3, 0
	v_mov_b32_e32 v4, 0
	v_mov_b32_e32 v5, 0
	v_mov_b32_e32 v6, 0
	v_mov_b32_e32 v7, 0
	v_mov_b32_e32 v8, 0
	v_mov_b32_e32 v9, 0
	v_mov_b32_e32 v10, 0
	v_mov_b32_e32 v11, 0
	v_mov_b32_e32 v12, 0
	v_mov_b32_e32 v13, 0
	v_mov_b32_e32 v14, 0
	v_mov_b32_e32 v15, 0
	v_mov_b32_e32 v16, 0
	v_mov_b32_e32 v17, 0
	v_mov_b32_e32 v18, 0
	v_mov_b32_e32 v19, 0
	v_mov_b32_e32 v20, 0
	v_mov_b32_e32 v21, 0
	v_mov_b32_e32 v22, 0
	v_mov_b32_e32 v23, 0
	v_mov_b32_e32 v24, 0
	v_mov_b32_e32 v25, 0
	v_mov_b32_e32 v26, 0
	v_mov_b32_e32 v27, 0
	v_mov_b32_e32 v28, 0
	v_mov_b32_e32 v29, 0
	v_mov_b32_e32 v30, 0
	v_mov_b32_e32 v31, 0
	v_mov_b32_e32 v32, 0
	v_mov_b32_e32 v33, 0
	v_mov_b32_e32 v34, 0
	v_mov_b32_e32 v35, 0
	v_mov_b32_e32 v36, 0
	v_mov_b32_e32 v37, 0
	v_mov_b32_e32 v38, 0
	v_mov_b32_e32 v39, 0
	v_mov_b32_e32 v40, 0
	v_mov_b32_e32 v41, 0
	v_mov_b32_e32 v42, 0
	v_mov_b32_e32 v43, 0
	v_mov_b32_e32 v44, 0
	v_mov_b32_e32 v45, 0
	v_mov_b32_e32 v46, 0
	v_mov_b32_e32 v47, 0
	v_mov_b32_e32 v48, 0
	v_mov_b32_e32 v49, 0
	v_mov_b32_e32 v50, 0
	v_mov_b32_e32 v51, 0
	v_mov_b32_e32 v52, 0
	v_mov_b32_e32 v53, 0
	v_mov_b32_e32 v54, 0
	v_mov_b32_e32 v55, 0
	v_mov_b32_e32 v56, 0
	v_mov_b32_e32 v57, 0
	v_mov_b32_e32 v58, 0
	v_mov_b32_e32 v59, 0
	v_mov_b32_e32 v60, 0
	v_mov_b32_e32 v61, 0
	v_mov_b32_e32 v62, 0
	v_mov_b32_e32 v63, 0
	s_waitcnt vmcnt(0)
	s_barrier
	s_add_u32 m0, s12, 0x6000
	ds_read_b128 v[96:99], v203 offset:0
	global_load_lds_dwordx4 v192, s[2:3]
	s_add_u32 m0, s12, 0x6400
	ds_read_b128 v[100:103], v203 offset:2048
	global_load_lds_dwordx4 v193, s[2:3]
	s_add_u32 m0, s12, 0x6800
	ds_read_b128 v[104:107], v203 offset:4096
	global_load_lds_dwordx4 v194, s[2:3]
	s_add_u32 m0, s12, 0x6c00
	ds_read_b128 v[108:111], v203 offset:6144
	global_load_lds_dwordx4 v195, s[2:3]
	s_add_u32 m0, s13, 0xa000
	ds_read_b128 v[128:131], v205 offset:16384
	global_load_lds_dwordx4 v196, s[4:5]
	s_add_u32 m0, s13, 0xa400
	ds_read_b128 v[132:135], v205 offset:18432
	global_load_lds_dwordx4 v197, s[4:5]
	s_add_u32 s2, s2, 0x80
	s_addc_u32 s3, s3, 0
	s_add_u32 s4, s4, 0x80
	s_addc_u32 s5, s5, 0
	ds_read_b128 v[112:115], v204 offset:0
	ds_read_b128 v[116:119], v204 offset:2048
	ds_read_b128 v[120:123], v204 offset:4096
	ds_read_b128 v[124:127], v204 offset:6144
	ds_read_b128 v[136:139], v206 offset:16384
	ds_read_b128 v[140:143], v206 offset:18432
	s_waitcnt lgkmcnt(0)
	s_mov_b32 s17, 0
.Lg4_nloop:
	s_waitcnt vmcnt(0)
	s_barrier
	v_mfma_f32_16x16x32_bf16 v[32:35], v[128:131], v[96:99], v[32:35]
	s_add_u32 m0, s12, 0x0
	ds_read_b128 v[144:147], v203 offset:24576
	v_mfma_f32_16x16x32_bf16 v[36:39], v[132:135], v[96:99], v[36:39]
	global_load_lds_dwordx4 v192, s[2:3]
	s_add_u32 m0, s12, 0x400
	ds_read_b128 v[148:151], v203 offset:26624
	v_mfma_f32_16x16x32_bf16 v[40:43], v[128:131], v[100:103], v[40:43]
	global_load_lds_dwordx4 v193, s[2:3]
	s_add_u32 m0, s12, 0x800
	ds_read_b128 v[152:155], v203 offset:28672
	v_mfma_f32_16x16x32_bf16 v[44:47], v[132:135], v[100:103], v[44:47]
	global_load_lds_dwordx4 v194, s[2:3]
	s_add_u32 m0, s12, 0xc00
	ds_read_b128 v[156:159], v203 offset:30720
	v_mfma_f32_16x16x32_bf16 v[48:51], v[128:131], v[104:107], v[48:51]
	global_load_lds_dwordx4 v195, s[2:3]
	s_add_u32 m0, s13, 0x4000
	ds_read_b128 v[176:179], v205 offset:40960
	v_mfma_f32_16x16x32_bf16 v[52:55], v[132:135], v[104:107], v[52:55]
	global_load_lds_dwordx4 v196, s[4:5]
	s_add_u32 m0, s13, 0x4400
	ds_read_b128 v[180:183], v205 offset:43008
	v_mfma_f32_16x16x32_bf16 v[56:59], v[128:131], v[108:111], v[56:59]
	global_load_lds_dwordx4 v197, s[4:5]
	ds_read_b128 v[160:163], v204 offset:24576
	v_mfma_f32_16x16x32_bf16 v[60:63], v[132:135], v[108:111], v[60:63]
	s_add_u32 s2, s2, 0x80
	s_addc_u32 s3, s3, 0
	ds_read_b128 v[164:167], v204 offset:26624
	v_mfma_f32_16x16x32_bf16 v[32:35], v[136:139], v[112:115], v[32:35]
	s_add_u32 s4, s4, 0x80
	s_addc_u32 s5, s5, 0
	ds_read_b128 v[168:171], v204 offset:28672
	v_mfma_f32_16x16x32_bf16 v[36:39], v[140:143], v[112:115], v[36:39]
	ds_read_b128 v[172:175], v204 offset:30720
	v_mfma_f32_16x16x32_bf16 v[40:43], v[136:139], v[116:119], v[40:43]
	ds_read_b128 v[184:187], v206 offset:40960
	v_mfma_f32_16x16x32_bf16 v[44:47], v[140:143], v[116:119], v[44:47]
	ds_read_b128 v[188:191], v206 offset:43008
	v_mfma_f32_16x16x32_bf16 v[48:51], v[136:139], v[120:123], v[48:51]
	v_mfma_f32_16x16x32_bf16 v[52:55], v[140:143], v[120:123], v[52:55]
	v_mfma_f32_16x16x32_bf16 v[56:59], v[136:139], v[124:127], v[56:59]
	v_mfma_f32_16x16x32_bf16 v[60:63], v[140:143], v[124:127], v[60:63]
	s_waitcnt lgkmcnt(0)
	s_waitcnt vmcnt(0)
	s_barrier
	v_mfma_f32_16x16x32_bf16 v[32:35], v[176:179], v[144:147], v[32:35]
	s_add_u32 m0, s12, 0x6000
	ds_read_b128 v[96:99], v203 offset:0
	v_mfma_f32_16x16x32_bf16 v[36:39], v[180:183], v[144:147], v[36:39]
	global_load_lds_dwordx4 v192, s[2:3]
	s_add_u32 m0, s12, 0x6400
	ds_read_b128 v[100:103], v203 offset:2048
	v_mfma_f32_16x16x32_bf16 v[40:43], v[176:179], v[148:151], v[40:43]
	global_load_lds_dwordx4 v193, s[2:3]
	s_add_u32 m0, s12, 0x6800
	ds_read_b128 v[104:107], v203 offset:4096
	v_mfma_f32_16x16x32_bf16 v[44:47], v[180:183], v[148:151], v[44:47]
	global_load_lds_dwordx4 v194, s[2:3]
	s_add_u32 m0, s12, 0x6c00
	ds_read_b128 v[108:111], v203 offset:6144
	v_mfma_f32_16x16x32_bf16 v[48:51], v[176:179], v[152:155], v[48:51]
	global_load_lds_dwordx4 v195, s[2:3]
	s_add_u32 m0, s13, 0xa000
	ds_read_b128 v[128:131], v205 offset:16384
	v_mfma_f32_16x16x32_bf16 v[52:55], v[180:183], v[152:155], v[52:55]
	global_load_lds_dwordx4 v196, s[4:5]
	s_add_u32 m0, s13, 0xa400
	ds_read_b128 v[132:135], v205 offset:18432
	v_mfma_f32_16x16x32_bf16 v[56:59], v[176:179], v[156:159], v[56:59]
	global_load_lds_dwordx4 v197, s[4:5]
	ds_read_b128 v[112:115], v204 offset:0
	v_mfma_f32_16x16x32_bf16 v[60:63], v[180:183], v[156:159], v[60:63]
	s_add_u32 s2, s2, 0x80
	s_addc_u32 s3, s3, 0
	ds_read_b128 v[116:119], v204 offset:2048
	v_mfma_f32_16x16x32_bf16 v[32:35], v[184:187], v[160:163], v[32:35]
	s_add_u32 s4, s4, 0x80
	s_addc_u32 s5, s5, 0
	ds_read_b128 v[120:123], v204 offset:4096
	v_mfma_f32_16x16x32_bf16 v[36:39], v[188:191], v[160:163], v[36:39]
	ds_read_b128 v[124:127], v204 offset:6144
	v_mfma_f32_16x16x32_bf16 v[40:43], v[184:187], v[164:167], v[40:43]
	ds_read_b128 v[136:139], v206 offset:16384
	v_mfma_f32_16x16x32_bf16 v[44:47], v[188:191], v[164:167], v[44:47]
	ds_read_b128 v[140:143], v206 offset:18432
	v_mfma_f32_16x16x32_bf16 v[48:51], v[184:187], v[168:171], v[48:51]
	v_mfma_f32_16x16x32_bf16 v[52:55], v[188:191], v[168:171], v[52:55]
	v_mfma_f32_16x16x32_bf16 v[56:59], v[184:187], v[172:175], v[56:59]
	v_mfma_f32_16x16x32_bf16 v[60:63], v[188:191], v[172:175], v[60:63]
	s_waitcnt lgkmcnt(0)
	s_waitcnt vmcnt(0)
	s_barrier
	v_mfma_f32_16x16x32_bf16 v[32:35], v[128:131], v[96:99], v[32:35]
	s_add_u32 m0, s12, 0x0
	ds_read_b128 v[144:147], v203 offset:24576
	v_mfma_f32_16x16x32_bf16 v[36:39], v[132:135], v[96:99], v[36:39]
	global_load_lds_dwordx4 v192, s[2:3]
	s_add_u32 m0, s12, 0x400
	ds_read_b128 v[148:151], v203 offset:26624
	v_mfma_f32_16x16x32_bf16 v[40:43], v[128:131], v[100:103], v[40:43]
	global_load_lds_dwordx4 v193, s[2:3]
	s_add_u32 m0, s12, 0x800
	ds_read_b128 v[152:155], v203 offset:28672
	v_mfma_f32_16x16x32_bf16 v[44:47], v[132:135], v[100:103], v[44:47]
	global_load_lds_dwordx4 v194, s[2:3]
	s_add_u32 m0, s12, 0xc00
	ds_read_b128 v[156:159], v203 offset:30720
	v_mfma_f32_16x16x32_bf16 v[48:51], v[128:131], v[104:107], v[48:51]
	global_load_lds_dwordx4 v195, s[2:3]
	s_add_u32 m0, s13, 0x4000
	ds_read_b128 v[176:179], v205 offset:40960
	v_mfma_f32_16x16x32_bf16 v[52:55], v[132:135], v[104:107], v[52:55]
	global_load_lds_dwordx4 v196, s[4:5]
	s_add_u32 m0, s13, 0x4400
	ds_read_b128 v[180:183], v205 offset:43008
	v_mfma_f32_16x16x32_bf16 v[56:59], v[128:131], v[108:111], v[56:59]
	global_load_lds_dwordx4 v197, s[4:5]
	ds_read_b128 v[160:163], v204 offset:24576
	v_mfma_f32_16x16x32_bf16 v[60:63], v[132:135], v[108:111], v[60:63]
	s_add_u32 s2, s2, 0x80
	s_addc_u32 s3, s3, 0
	ds_read_b128 v[164:167], v204 offset:26624
	v_mfma_f32_16x16x32_bf16 v[32:35], v[136:139], v[112:115], v[32:35]
	s_add_u32 s4, s4, 0x80
	s_addc_u32 s5, s5, 0
	ds_read_b128 v[168:171], v204 offset:28672
	v_mfma_f32_16x16x32_bf16 v[36:39], v[140:143], v[112:115], v[36:39]
	ds_read_b128 v[172:175], v204 offset:30720
	v_mfma_f32_16x16x32_bf16 v[40:43], v[136:139], v[116:119], v[40:43]
	ds_read_b128 v[184:187], v206 offset:40960
	v_mfma_f32_16x16x32_bf16 v[44:47], v[140:143], v[116:119], v[44:47]
	ds_read_b128 v[188:191], v206 offset:43008
	v_mfma_f32_16x16x32_bf16 v[48:51], v[136:139], v[120:123], v[48:51]
	v_mfma_f32_16x16x32_bf16 v[52:55], v[140:143], v[120:123], v[52:55]
	v_mfma_f32_16x16x32_bf16 v[56:59], v[136:139], v[124:127], v[56:59]
	v_mfma_f32_16x16x32_bf16 v[60:63], v[140:143], v[124:127], v[60:63]
	s_waitcnt lgkmcnt(0)
	s_waitcnt vmcnt(0)
	s_barrier
	v_mfma_f32_16x16x32_bf16 v[32:35], v[176:179], v[144:147], v[32:35]
	s_add_u32 m0, s12, 0x6000
	ds_read_b128 v[96:99], v203 offset:0
	v_mfma_f32_16x16x32_bf16 v[36:39], v[180:183], v[144:147], v[36:39]
	global_load_lds_dwordx4 v192, s[2:3]
	s_add_u32 m0, s12, 0x6400
	ds_read_b128 v[100:103], v203 offset:2048
	v_mfma_f32_16x16x32_bf16 v[40:43], v[176:179], v[148:151], v[40:43]
	global_load_lds_dwordx4 v193, s[2:3]
	s_add_u32 m0, s12, 0x6800
	ds_read_b128 v[104:107], v203 offset:4096
	v_mfma_f32_16x16x32_bf16 v[44:47], v[180:183], v[148:151], v[44:47]
	global_load_lds_dwordx4 v194, s[2:3]
	s_add_u32 m0, s12, 0x6c00
	ds_read_b128 v[108:111], v203 offset:6144
	v_mfma_f32_16x16x32_bf16 v[48:51], v[176:179], v[152:155], v[48:51]
	global_load_lds_dwordx4 v195, s[2:3]
	s_add_u32 m0, s13, 0xa000
	ds_read_b128 v[128:131], v205 offset:16384
	v_mfma_f32_16x16x32_bf16 v[52:55], v[180:183], v[152:155], v[52:55]
	global_load_lds_dwordx4 v196, s[4:5]
	s_add_u32 m0, s13, 0xa400
	ds_read_b128 v[132:135], v205 offset:18432
	v_mfma_f32_16x16x32_bf16 v[56:59], v[176:179], v[156:159], v[56:59]
	global_load_lds_dwordx4 v197, s[4:5]
	ds_read_b128 v[112:115], v204 offset:0
	v_mfma_f32_16x16x32_bf16 v[60:63], v[180:183], v[156:159], v[60:63]
	s_add_u32 s2, s2, 0x80
	s_addc_u32 s3, s3, 0
	ds_read_b128 v[116:119], v204 offset:2048
	v_mfma_f32_16x16x32_bf16 v[32:35], v[184:187], v[160:163], v[32:35]
	s_add_u32 s4, s4, 0x80
	s_addc_u32 s5, s5, 0
	ds_read_b128 v[120:123], v204 offset:4096
	v_mfma_f32_16x16x32_bf16 v[36:39], v[188:191], v[160:163], v[36:39]
	ds_read_b128 v[124:127], v204 offset:6144
	v_mfma_f32_16x16x32_bf16 v[40:43], v[184:187], v[164:167], v[40:43]
	ds_read_b128 v[136:139], v206 offset:16384
	v_mfma_f32_16x16x32_bf16 v[44:47], v[188:191], v[164:167], v[44:47]
	ds_read_b128 v[140:143], v206 offset:18432
	v_mfma_f32_16x16x32_bf16 v[48:51], v[184:187], v[168:171], v[48:51]
	v_mfma_f32_16x16x32_bf16 v[52:55], v[188:191], v[168:171], v[52:55]
	v_mfma_f32_16x16x32_bf16 v[56:59], v[184:187], v[172:175], v[56:59]
	v_mfma_f32_16x16x32_bf16 v[60:63], v[188:191], v[172:175], v[60:63]
	s_waitcnt lgkmcnt(0)
	s_waitcnt vmcnt(0)
	s_barrier
	v_mfma_f32_16x16x32_bf16 v[32:35], v[128:131], v[96:99], v[32:35]
	s_add_u32 m0, s12, 0x0
	ds_read_b128 v[144:147], v203 offset:24576
	v_mfma_f32_16x16x32_bf16 v[36:39], v[132:135], v[96:99], v[36:39]
	global_load_lds_dwordx4 v192, s[2:3]
	s_add_u32 m0, s12, 0x400
	ds_read_b128 v[148:151], v203 offset:26624
	v_mfma_f32_16x16x32_bf16 v[40:43], v[128:131], v[100:103], v[40:43]
	global_load_lds_dwordx4 v193, s[2:3]
	s_add_u32 m0, s12, 0x800
	ds_read_b128 v[152:155], v203 offset:28672
	v_mfma_f32_16x16x32_bf16 v[44:47], v[132:135], v[100:103], v[44:47]
	global_load_lds_dwordx4 v194, s[2:3]
	s_add_u32 m0, s12, 0xc00
	ds_read_b128 v[156:159], v203 offset:30720
	v_mfma_f32_16x16x32_bf16 v[48:51], v[128:131], v[104:107], v[48:51]
	global_load_lds_dwordx4 v195, s[2:3]
	s_add_u32 m0, s13, 0x4000
	ds_read_b128 v[176:179], v205 offset:40960
	v_mfma_f32_16x16x32_bf16 v[52:55], v[132:135], v[104:107], v[52:55]
	global_load_lds_dwordx4 v196, s[4:5]
	s_add_u32 m0, s13, 0x4400
	ds_read_b128 v[180:183], v205 offset:43008
	v_mfma_f32_16x16x32_bf16 v[56:59], v[128:131], v[108:111], v[56:59]
	global_load_lds_dwordx4 v197, s[4:5]
	ds_read_b128 v[160:163], v204 offset:24576
	v_mfma_f32_16x16x32_bf16 v[60:63], v[132:135], v[108:111], v[60:63]
	s_add_u32 s2, s2, 0x80
	s_addc_u32 s3, s3, 0
	ds_read_b128 v[164:167], v204 offset:26624
	v_mfma_f32_16x16x32_bf16 v[32:35], v[136:139], v[112:115], v[32:35]
	s_add_u32 s4, s4, 0x80
	s_addc_u32 s5, s5, 0
	ds_read_b128 v[168:171], v204 offset:28672
	v_mfma_f32_16x16x32_bf16 v[36:39], v[140:143], v[112:115], v[36:39]
	ds_read_b128 v[172:175], v204 offset:30720
	v_mfma_f32_16x16x32_bf16 v[40:43], v[136:139], v[116:119], v[40:43]
	ds_read_b128 v[184:187], v206 offset:40960
	v_mfma_f32_16x16x32_bf16 v[44:47], v[140:143], v[116:119], v[44:47]
	ds_read_b128 v[188:191], v206 offset:43008
	v_mfma_f32_16x16x32_bf16 v[48:51], v[136:139], v[120:123], v[48:51]
	v_mfma_f32_16x16x32_bf16 v[52:55], v[140:143], v[120:123], v[52:55]
	v_mfma_f32_16x16x32_bf16 v[56:59], v[136:139], v[124:127], v[56:59]
	v_mfma_f32_16x16x32_bf16 v[60:63], v[140:143], v[124:127], v[60:63]
	s_waitcnt lgkmcnt(0)
	s_waitcnt vmcnt(0)
	s_barrier
	v_mfma_f32_16x16x32_bf16 v[32:35], v[176:179], v[144:147], v[32:35]
	s_add_u32 m0, s12, 0x6000
	ds_read_b128 v[96:99], v203 offset:0
	v_mfma_f32_16x16x32_bf16 v[36:39], v[180:183], v[144:147], v[36:39]
	global_load_lds_dwordx4 v192, s[2:3]
	s_add_u32 m0, s12, 0x6400
	ds_read_b128 v[100:103], v203 offset:2048
	v_mfma_f32_16x16x32_bf16 v[40:43], v[176:179], v[148:151], v[40:43]
	global_load_lds_dwordx4 v193, s[2:3]
	s_add_u32 m0, s12, 0x6800
	ds_read_b128 v[104:107], v203 offset:4096
	v_mfma_f32_16x16x32_bf16 v[44:47], v[180:183], v[148:151], v[44:47]
	global_load_lds_dwordx4 v194, s[2:3]
	s_add_u32 m0, s12, 0x6c00
	ds_read_b128 v[108:111], v203 offset:6144
	v_mfma_f32_16x16x32_bf16 v[48:51], v[176:179], v[152:155], v[48:51]
	global_load_lds_dwordx4 v195, s[2:3]
	s_add_u32 m0, s13, 0xa000
	ds_read_b128 v[128:131], v205 offset:16384
	v_mfma_f32_16x16x32_bf16 v[52:55], v[180:183], v[152:155], v[52:55]
	global_load_lds_dwordx4 v196, s[4:5]
	s_add_u32 m0, s13, 0xa400
	ds_read_b128 v[132:135], v205 offset:18432
	v_mfma_f32_16x16x32_bf16 v[56:59], v[176:179], v[156:159], v[56:59]
	global_load_lds_dwordx4 v197, s[4:5]
	ds_read_b128 v[112:115], v204 offset:0
	v_mfma_f32_16x16x32_bf16 v[60:63], v[180:183], v[156:159], v[60:63]
	s_add_u32 s2, s2, 0x80
	s_addc_u32 s3, s3, 0
	ds_read_b128 v[116:119], v204 offset:2048
	v_mfma_f32_16x16x32_bf16 v[32:35], v[184:187], v[160:163], v[32:35]
	s_add_u32 s4, s4, 0x80
	s_addc_u32 s5, s5, 0
	ds_read_b128 v[120:123], v204 offset:4096
	v_mfma_f32_16x16x32_bf16 v[36:39], v[188:191], v[160:163], v[36:39]
	ds_read_b128 v[124:127], v204 offset:6144
	v_mfma_f32_16x16x32_bf16 v[40:43], v[184:187], v[164:167], v[40:43]
	ds_read_b128 v[136:139], v206 offset:16384
	v_mfma_f32_16x16x32_bf16 v[44:47], v[188:191], v[164:167], v[44:47]
	ds_read_b128 v[140:143], v206 offset:18432
	v_mfma_f32_16x16x32_bf16 v[48:51], v[184:187], v[168:171], v[48:51]
	v_mfma_f32_16x16x32_bf16 v[52:55], v[188:191], v[168:171], v[52:55]
	v_mfma_f32_16x16x32_bf16 v[56:59], v[184:187], v[172:175], v[56:59]
	v_mfma_f32_16x16x32_bf16 v[60:63], v[188:191], v[172:175], v[60:63]
	s_waitcnt lgkmcnt(0)
	s_waitcnt vmcnt(0)
	s_barrier
	v_mfma_f32_16x16x32_bf16 v[32:35], v[128:131], v[96:99], v[32:35]
	s_add_u32 m0, s12, 0x0
	ds_read_b128 v[144:147], v203 offset:24576
	v_mfma_f32_16x16x32_bf16 v[36:39], v[132:135], v[96:99], v[36:39]
	global_load_lds_dwordx4 v192, s[2:3]
	s_add_u32 m0, s12, 0x400
	ds_read_b128 v[148:151], v203 offset:26624
	v_mfma_f32_16x16x32_bf16 v[40:43], v[128:131], v[100:103], v[40:43]
	global_load_lds_dwordx4 v193, s[2:3]
	s_add_u32 m0, s12, 0x800
	ds_read_b128 v[152:155], v203 offset:28672
	v_mfma_f32_16x16x32_bf16 v[44:47], v[132:135], v[100:103], v[44:47]
	global_load_lds_dwordx4 v194, s[2:3]
	s_add_u32 m0, s12, 0xc00
	ds_read_b128 v[156:159], v203 offset:30720
	v_mfma_f32_16x16x32_bf16 v[48:51], v[128:131], v[104:107], v[48:51]
	global_load_lds_dwordx4 v195, s[2:3]
	s_add_u32 m0, s13, 0x4000
	ds_read_b128 v[176:179], v205 offset:40960
	v_mfma_f32_16x16x32_bf16 v[52:55], v[132:135], v[104:107], v[52:55]
	global_load_lds_dwordx4 v196, s[4:5]
	s_add_u32 m0, s13, 0x4400
	ds_read_b128 v[180:183], v205 offset:43008
	v_mfma_f32_16x16x32_bf16 v[56:59], v[128:131], v[108:111], v[56:59]
	global_load_lds_dwordx4 v197, s[4:5]
	ds_read_b128 v[160:163], v204 offset:24576
	v_mfma_f32_16x16x32_bf16 v[60:63], v[132:135], v[108:111], v[60:63]
	s_add_u32 s2, s2, 0x80
	s_addc_u32 s3, s3, 0
	ds_read_b128 v[164:167], v204 offset:26624
	v_mfma_f32_16x16x32_bf16 v[32:35], v[136:139], v[112:115], v[32:35]
	s_add_u32 s4, s4, 0x80
	s_addc_u32 s5, s5, 0
	ds_read_b128 v[168:171], v204 offset:28672
	v_mfma_f32_16x16x32_bf16 v[36:39], v[140:143], v[112:115], v[36:39]
	ds_read_b128 v[172:175], v204 offset:30720
	v_mfma_f32_16x16x32_bf16 v[40:43], v[136:139], v[116:119], v[40:43]
	ds_read_b128 v[184:187], v206 offset:40960
	v_mfma_f32_16x16x32_bf16 v[44:47], v[140:143], v[116:119], v[44:47]
	ds_read_b128 v[188:191], v206 offset:43008
	v_mfma_f32_16x16x32_bf16 v[48:51], v[136:139], v[120:123], v[48:51]
	v_mfma_f32_16x16x32_bf16 v[52:55], v[140:143], v[120:123], v[52:55]
	v_mfma_f32_16x16x32_bf16 v[56:59], v[136:139], v[124:127], v[56:59]
	v_mfma_f32_16x16x32_bf16 v[60:63], v[140:143], v[124:127], v[60:63]
	s_waitcnt lgkmcnt(0)
	s_waitcnt vmcnt(0)
	s_barrier
	v_mfma_f32_16x16x32_bf16 v[32:35], v[176:179], v[144:147], v[32:35]
	s_add_u32 m0, s12, 0x6000
	ds_read_b128 v[96:99], v203 offset:0
	v_mfma_f32_16x16x32_bf16 v[36:39], v[180:183], v[144:147], v[36:39]
	global_load_lds_dwordx4 v192, s[2:3]
	s_add_u32 m0, s12, 0x6400
	ds_read_b128 v[100:103], v203 offset:2048
	v_mfma_f32_16x16x32_bf16 v[40:43], v[176:179], v[148:151], v[40:43]
	global_load_lds_dwordx4 v193, s[2:3]
	s_add_u32 m0, s12, 0x6800
	ds_read_b128 v[104:107], v203 offset:4096
	v_mfma_f32_16x16x32_bf16 v[44:47], v[180:183], v[148:151], v[44:47]
	global_load_lds_dwordx4 v194, s[2:3]
	s_add_u32 m0, s12, 0x6c00
	ds_read_b128 v[108:111], v203 offset:6144
	v_mfma_f32_16x16x32_bf16 v[48:51], v[176:179], v[152:155], v[48:51]
	global_load_lds_dwordx4 v195, s[2:3]
	s_add_u32 m0, s13, 0xa000
	ds_read_b128 v[128:131], v205 offset:16384
	v_mfma_f32_16x16x32_bf16 v[52:55], v[180:183], v[152:155], v[52:55]
	global_load_lds_dwordx4 v196, s[4:5]
	s_add_u32 m0, s13, 0xa400
	ds_read_b128 v[132:135], v205 offset:18432
	v_mfma_f32_16x16x32_bf16 v[56:59], v[176:179], v[156:159], v[56:59]
	global_load_lds_dwordx4 v197, s[4:5]
	ds_read_b128 v[112:115], v204 offset:0
	v_mfma_f32_16x16x32_bf16 v[60:63], v[180:183], v[156:159], v[60:63]
	s_add_u32 s2, s2, 0x80
	s_addc_u32 s3, s3, 0
	ds_read_b128 v[116:119], v204 offset:2048
	v_mfma_f32_16x16x32_bf16 v[32:35], v[184:187], v[160:163], v[32:35]
	s_add_u32 s4, s4, 0x80
	s_addc_u32 s5, s5, 0
	ds_read_b128 v[120:123], v204 offset:4096
	v_mfma_f32_16x16x32_bf16 v[36:39], v[188:191], v[160:163], v[36:39]
	ds_read_b128 v[124:127], v204 offset:6144
	v_mfma_f32_16x16x32_bf16 v[40:43], v[184:187], v[164:167], v[40:43]
	ds_read_b128 v[136:139], v206 offset:16384
	v_mfma_f32_16x16x32_bf16 v[44:47], v[188:191], v[164:167], v[44:47]
	ds_read_b128 v[140:143], v206 offset:18432
	v_mfma_f32_16x16x32_bf16 v[48:51], v[184:187], v[168:171], v[48:51]
	v_mfma_f32_16x16x32_bf16 v[52:55], v[188:191], v[168:171], v[52:55]
	v_mfma_f32_16x16x32_bf16 v[56:59], v[184:187], v[172:175], v[56:59]
	v_mfma_f32_16x16x32_bf16 v[60:63], v[188:191], v[172:175], v[60:63]
	s_waitcnt lgkmcnt(0)
	s_waitcnt vmcnt(0)
	s_barrier
	v_mfma_f32_16x16x32_bf16 v[32:35], v[128:131], v[96:99], v[32:35]
	s_add_u32 m0, s12, 0x0
	ds_read_b128 v[144:147], v203 offset:24576
	v_mfma_f32_16x16x32_bf16 v[36:39], v[132:135], v[96:99], v[36:39]
	global_load_lds_dwordx4 v192, s[2:3]
	s_add_u32 m0, s12, 0x400
	ds_read_b128 v[148:151], v203 offset:26624
	v_mfma_f32_16x16x32_bf16 v[40:43], v[128:131], v[100:103], v[40:43]
	global_load_lds_dwordx4 v193, s[2:3]
	s_add_u32 m0, s12, 0x800
	ds_read_b128 v[152:155], v203 offset:28672
	v_mfma_f32_16x16x32_bf16 v[44:47], v[132:135], v[100:103], v[44:47]
	global_load_lds_dwordx4 v194, s[2:3]
	s_add_u32 m0, s12, 0xc00
	ds_read_b128 v[156:159], v203 offset:30720
	v_mfma_f32_16x16x32_bf16 v[48:51], v[128:131], v[104:107], v[48:51]
	global_load_lds_dwordx4 v195, s[2:3]
	s_add_u32 m0, s13, 0x4000
	ds_read_b128 v[176:179], v205 offset:40960
	v_mfma_f32_16x16x32_bf16 v[52:55], v[132:135], v[104:107], v[52:55]
	global_load_lds_dwordx4 v196, s[4:5]
	s_add_u32 m0, s13, 0x4400
	ds_read_b128 v[180:183], v205 offset:43008
	v_mfma_f32_16x16x32_bf16 v[56:59], v[128:131], v[108:111], v[56:59]
	global_load_lds_dwordx4 v197, s[4:5]
	ds_read_b128 v[160:163], v204 offset:24576
	v_mfma_f32_16x16x32_bf16 v[60:63], v[132:135], v[108:111], v[60:63]
	s_add_u32 s2, s2, 0x80
	s_addc_u32 s3, s3, 0
	ds_read_b128 v[164:167], v204 offset:26624
	v_mfma_f32_16x16x32_bf16 v[32:35], v[136:139], v[112:115], v[32:35]
	s_add_u32 s4, s4, 0x80
	s_addc_u32 s5, s5, 0
	ds_read_b128 v[168:171], v204 offset:28672
	v_mfma_f32_16x16x32_bf16 v[36:39], v[140:143], v[112:115], v[36:39]
	ds_read_b128 v[172:175], v204 offset:30720
	v_mfma_f32_16x16x32_bf16 v[40:43], v[136:139], v[116:119], v[40:43]
	ds_read_b128 v[184:187], v206 offset:40960
	v_mfma_f32_16x16x32_bf16 v[44:47], v[140:143], v[116:119], v[44:47]
	ds_read_b128 v[188:191], v206 offset:43008
	v_mfma_f32_16x16x32_bf16 v[48:51], v[136:139], v[120:123], v[48:51]
	v_mfma_f32_16x16x32_bf16 v[52:55], v[140:143], v[120:123], v[52:55]
	v_mfma_f32_16x16x32_bf16 v[56:59], v[136:139], v[124:127], v[56:59]
	v_mfma_f32_16x16x32_bf16 v[60:63], v[140:143], v[124:127], v[60:63]
	s_waitcnt lgkmcnt(0)
	s_waitcnt vmcnt(0)
	s_barrier
	v_mfma_f32_16x16x32_bf16 v[32:35], v[176:179], v[144:147], v[32:35]
	s_add_u32 m0, s12, 0x6000
	ds_read_b128 v[96:99], v203 offset:0
	v_mfma_f32_16x16x32_bf16 v[36:39], v[180:183], v[144:147], v[36:39]
	global_load_lds_dwordx4 v192, s[2:3]
	s_add_u32 m0, s12, 0x6400
	ds_read_b128 v[100:103], v203 offset:2048
	v_mfma_f32_16x16x32_bf16 v[40:43], v[176:179], v[148:151], v[40:43]
	global_load_lds_dwordx4 v193, s[2:3]
	s_add_u32 m0, s12, 0x6800
	ds_read_b128 v[104:107], v203 offset:4096
	v_mfma_f32_16x16x32_bf16 v[44:47], v[180:183], v[148:151], v[44:47]
	global_load_lds_dwordx4 v194, s[2:3]
	s_add_u32 m0, s12, 0x6c00
	ds_read_b128 v[108:111], v203 offset:6144
	v_mfma_f32_16x16x32_bf16 v[48:51], v[176:179], v[152:155], v[48:51]
	global_load_lds_dwordx4 v195, s[2:3]
	s_add_u32 m0, s13, 0xa000
	ds_read_b128 v[128:131], v205 offset:16384
	v_mfma_f32_16x16x32_bf16 v[52:55], v[180:183], v[152:155], v[52:55]
	global_load_lds_dwordx4 v196, s[4:5]
	s_add_u32 m0, s13, 0xa400
	ds_read_b128 v[132:135], v205 offset:18432
	v_mfma_f32_16x16x32_bf16 v[56:59], v[176:179], v[156:159], v[56:59]
	global_load_lds_dwordx4 v197, s[4:5]
	ds_read_b128 v[112:115], v204 offset:0
	v_mfma_f32_16x16x32_bf16 v[60:63], v[180:183], v[156:159], v[60:63]
	s_add_u32 s2, s2, 0x80
	s_addc_u32 s3, s3, 0
	ds_read_b128 v[116:119], v204 offset:2048
	v_mfma_f32_16x16x32_bf16 v[32:35], v[184:187], v[160:163], v[32:35]
	s_add_u32 s4, s4, 0x80
	s_addc_u32 s5, s5, 0
	ds_read_b128 v[120:123], v204 offset:4096
	v_mfma_f32_16x16x32_bf16 v[36:39], v[188:191], v[160:163], v[36:39]
	ds_read_b128 v[124:127], v204 offset:6144
	v_mfma_f32_16x16x32_bf16 v[40:43], v[184:187], v[164:167], v[40:43]
	ds_read_b128 v[136:139], v206 offset:16384
	v_mfma_f32_16x16x32_bf16 v[44:47], v[188:191], v[164:167], v[44:47]
	ds_read_b128 v[140:143], v206 offset:18432
	v_mfma_f32_16x16x32_bf16 v[48:51], v[184:187], v[168:171], v[48:51]
	v_mfma_f32_16x16x32_bf16 v[52:55], v[188:191], v[168:171], v[52:55]
	v_mfma_f32_16x16x32_bf16 v[56:59], v[184:187], v[172:175], v[56:59]
	v_mfma_f32_16x16x32_bf16 v[60:63], v[188:191], v[172:175], v[60:63]
	s_waitcnt lgkmcnt(0)
	s_waitcnt vmcnt(0)
	s_barrier
	v_mfma_f32_16x16x32_bf16 v[32:35], v[128:131], v[96:99], v[32:35]
	s_add_u32 m0, s12, 0x0
	ds_read_b128 v[144:147], v203 offset:24576
	v_mfma_f32_16x16x32_bf16 v[36:39], v[132:135], v[96:99], v[36:39]
	global_load_lds_dwordx4 v192, s[2:3]
	s_add_u32 m0, s12, 0x400
	ds_read_b128 v[148:151], v203 offset:26624
	v_mfma_f32_16x16x32_bf16 v[40:43], v[128:131], v[100:103], v[40:43]
	global_load_lds_dwordx4 v193, s[2:3]
	s_add_u32 m0, s12, 0x800
	ds_read_b128 v[152:155], v203 offset:28672
	v_mfma_f32_16x16x32_bf16 v[44:47], v[132:135], v[100:103], v[44:47]
	global_load_lds_dwordx4 v194, s[2:3]
	s_add_u32 m0, s12, 0xc00
	ds_read_b128 v[156:159], v203 offset:30720
	v_mfma_f32_16x16x32_bf16 v[48:51], v[128:131], v[104:107], v[48:51]
	global_load_lds_dwordx4 v195, s[2:3]
	s_add_u32 m0, s13, 0x4000
	ds_read_b128 v[176:179], v205 offset:40960
	v_mfma_f32_16x16x32_bf16 v[52:55], v[132:135], v[104:107], v[52:55]
	global_load_lds_dwordx4 v196, s[4:5]
	s_add_u32 m0, s13, 0x4400
	ds_read_b128 v[180:183], v205 offset:43008
	v_mfma_f32_16x16x32_bf16 v[56:59], v[128:131], v[108:111], v[56:59]
	global_load_lds_dwordx4 v197, s[4:5]
	ds_read_b128 v[160:163], v204 offset:24576
	v_mfma_f32_16x16x32_bf16 v[60:63], v[132:135], v[108:111], v[60:63]
	s_add_u32 s2, s2, 0x80
	s_addc_u32 s3, s3, 0
	ds_read_b128 v[164:167], v204 offset:26624
	v_mfma_f32_16x16x32_bf16 v[32:35], v[136:139], v[112:115], v[32:35]
	s_add_u32 s4, s4, 0x80
	s_addc_u32 s5, s5, 0
	ds_read_b128 v[168:171], v204 offset:28672
	v_mfma_f32_16x16x32_bf16 v[36:39], v[140:143], v[112:115], v[36:39]
	ds_read_b128 v[172:175], v204 offset:30720
	v_mfma_f32_16x16x32_bf16 v[40:43], v[136:139], v[116:119], v[40:43]
	ds_read_b128 v[184:187], v206 offset:40960
	v_mfma_f32_16x16x32_bf16 v[44:47], v[140:143], v[116:119], v[44:47]
	ds_read_b128 v[188:191], v206 offset:43008
	v_mfma_f32_16x16x32_bf16 v[48:51], v[136:139], v[120:123], v[48:51]
	v_mfma_f32_16x16x32_bf16 v[52:55], v[140:143], v[120:123], v[52:55]
	v_mfma_f32_16x16x32_bf16 v[56:59], v[136:139], v[124:127], v[56:59]
	v_mfma_f32_16x16x32_bf16 v[60:63], v[140:143], v[124:127], v[60:63]
	s_waitcnt lgkmcnt(0)
	s_waitcnt vmcnt(0)
	s_barrier
	v_mfma_f32_16x16x32_bf16 v[32:35], v[176:179], v[144:147], v[32:35]
	s_add_u32 m0, s12, 0x6000
	ds_read_b128 v[96:99], v203 offset:0
	v_mfma_f32_16x16x32_bf16 v[36:39], v[180:183], v[144:147], v[36:39]
	global_load_lds_dwordx4 v192, s[2:3]
	s_add_u32 m0, s12, 0x6400
	ds_read_b128 v[100:103], v203 offset:2048
	v_mfma_f32_16x16x32_bf16 v[40:43], v[176:179], v[148:151], v[40:43]
	global_load_lds_dwordx4 v193, s[2:3]
	s_add_u32 m0, s12, 0x6800
	ds_read_b128 v[104:107], v203 offset:4096
	v_mfma_f32_16x16x32_bf16 v[44:47], v[180:183], v[148:151], v[44:47]
	global_load_lds_dwordx4 v194, s[2:3]
	s_add_u32 m0, s12, 0x6c00
	ds_read_b128 v[108:111], v203 offset:6144
	v_mfma_f32_16x16x32_bf16 v[48:51], v[176:179], v[152:155], v[48:51]
	global_load_lds_dwordx4 v195, s[2:3]
	s_add_u32 m0, s13, 0xa000
	ds_read_b128 v[128:131], v205 offset:16384
	v_mfma_f32_16x16x32_bf16 v[52:55], v[180:183], v[152:155], v[52:55]
	global_load_lds_dwordx4 v196, s[4:5]
	s_add_u32 m0, s13, 0xa400
	ds_read_b128 v[132:135], v205 offset:18432
	v_mfma_f32_16x16x32_bf16 v[56:59], v[176:179], v[156:159], v[56:59]
	global_load_lds_dwordx4 v197, s[4:5]
	ds_read_b128 v[112:115], v204 offset:0
	v_mfma_f32_16x16x32_bf16 v[60:63], v[180:183], v[156:159], v[60:63]
	s_add_u32 s2, s2, 0x80
	s_addc_u32 s3, s3, 0
	ds_read_b128 v[116:119], v204 offset:2048
	v_mfma_f32_16x16x32_bf16 v[32:35], v[184:187], v[160:163], v[32:35]
	s_add_u32 s4, s4, 0x80
	s_addc_u32 s5, s5, 0
	ds_read_b128 v[120:123], v204 offset:4096
	v_mfma_f32_16x16x32_bf16 v[36:39], v[188:191], v[160:163], v[36:39]
	ds_read_b128 v[124:127], v204 offset:6144
	v_mfma_f32_16x16x32_bf16 v[40:43], v[184:187], v[164:167], v[40:43]
	ds_read_b128 v[136:139], v206 offset:16384
	v_mfma_f32_16x16x32_bf16 v[44:47], v[188:191], v[164:167], v[44:47]
	ds_read_b128 v[140:143], v206 offset:18432
	v_mfma_f32_16x16x32_bf16 v[48:51], v[184:187], v[168:171], v[48:51]
	v_mfma_f32_16x16x32_bf16 v[52:55], v[188:191], v[168:171], v[52:55]
	v_mfma_f32_16x16x32_bf16 v[56:59], v[184:187], v[172:175], v[56:59]
	v_mfma_f32_16x16x32_bf16 v[60:63], v[188:191], v[172:175], v[60:63]
	s_waitcnt lgkmcnt(0)
	s_waitcnt vmcnt(0)
	s_barrier
	v_mfma_f32_16x16x32_bf16 v[32:35], v[128:131], v[96:99], v[32:35]
	s_add_u32 m0, s12, 0x0
	ds_read_b128 v[144:147], v203 offset:24576
	v_mfma_f32_16x16x32_bf16 v[36:39], v[132:135], v[96:99], v[36:39]
	global_load_lds_dwordx4 v192, s[2:3]
	s_add_u32 m0, s12, 0x400
	ds_read_b128 v[148:151], v203 offset:26624
	v_mfma_f32_16x16x32_bf16 v[40:43], v[128:131], v[100:103], v[40:43]
	global_load_lds_dwordx4 v193, s[2:3]
	s_add_u32 m0, s12, 0x800
	ds_read_b128 v[152:155], v203 offset:28672
	v_mfma_f32_16x16x32_bf16 v[44:47], v[132:135], v[100:103], v[44:47]
	global_load_lds_dwordx4 v194, s[2:3]
	s_add_u32 m0, s12, 0xc00
	ds_read_b128 v[156:159], v203 offset:30720
	v_mfma_f32_16x16x32_bf16 v[48:51], v[128:131], v[104:107], v[48:51]
	global_load_lds_dwordx4 v195, s[2:3]
	s_add_u32 m0, s13, 0x4000
	ds_read_b128 v[176:179], v205 offset:40960
	v_mfma_f32_16x16x32_bf16 v[52:55], v[132:135], v[104:107], v[52:55]
	global_load_lds_dwordx4 v196, s[4:5]
	s_add_u32 m0, s13, 0x4400
	ds_read_b128 v[180:183], v205 offset:43008
	v_mfma_f32_16x16x32_bf16 v[56:59], v[128:131], v[108:111], v[56:59]
	global_load_lds_dwordx4 v197, s[4:5]
	ds_read_b128 v[160:163], v204 offset:24576
	v_mfma_f32_16x16x32_bf16 v[60:63], v[132:135], v[108:111], v[60:63]
	s_add_u32 s2, s2, 0x80
	s_addc_u32 s3, s3, 0
	ds_read_b128 v[164:167], v204 offset:26624
	v_mfma_f32_16x16x32_bf16 v[32:35], v[136:139], v[112:115], v[32:35]
	s_add_u32 s4, s4, 0x80
	s_addc_u32 s5, s5, 0
	ds_read_b128 v[168:171], v204 offset:28672
	v_mfma_f32_16x16x32_bf16 v[36:39], v[140:143], v[112:115], v[36:39]
	ds_read_b128 v[172:175], v204 offset:30720
	v_mfma_f32_16x16x32_bf16 v[40:43], v[136:139], v[116:119], v[40:43]
	ds_read_b128 v[184:187], v206 offset:40960
	v_mfma_f32_16x16x32_bf16 v[44:47], v[140:143], v[116:119], v[44:47]
	ds_read_b128 v[188:191], v206 offset:43008
	v_mfma_f32_16x16x32_bf16 v[48:51], v[136:139], v[120:123], v[48:51]
	v_mfma_f32_16x16x32_bf16 v[52:55], v[140:143], v[120:123], v[52:55]
	v_mfma_f32_16x16x32_bf16 v[56:59], v[136:139], v[124:127], v[56:59]
	v_mfma_f32_16x16x32_bf16 v[60:63], v[140:143], v[124:127], v[60:63]
	s_waitcnt lgkmcnt(0)
	s_waitcnt vmcnt(0)
	s_barrier
	v_mfma_f32_16x16x32_bf16 v[32:35], v[176:179], v[144:147], v[32:35]
	s_add_u32 m0, s12, 0x6000
	ds_read_b128 v[96:99], v203 offset:0
	v_mfma_f32_16x16x32_bf16 v[36:39], v[180:183], v[144:147], v[36:39]
	global_load_lds_dwordx4 v192, s[2:3]
	s_add_u32 m0, s12, 0x6400
	ds_read_b128 v[100:103], v203 offset:2048
	v_mfma_f32_16x16x32_bf16 v[40:43], v[176:179], v[148:151], v[40:43]
	global_load_lds_dwordx4 v193, s[2:3]
	s_add_u32 m0, s12, 0x6800
	ds_read_b128 v[104:107], v203 offset:4096
	v_mfma_f32_16x16x32_bf16 v[44:47], v[180:183], v[148:151], v[44:47]
	global_load_lds_dwordx4 v194, s[2:3]
	s_add_u32 m0, s12, 0x6c00
	ds_read_b128 v[108:111], v203 offset:6144
	v_mfma_f32_16x16x32_bf16 v[48:51], v[176:179], v[152:155], v[48:51]
	global_load_lds_dwordx4 v195, s[2:3]
	s_add_u32 m0, s13, 0xa000
	ds_read_b128 v[128:131], v205 offset:16384
	v_mfma_f32_16x16x32_bf16 v[52:55], v[180:183], v[152:155], v[52:55]
	global_load_lds_dwordx4 v196, s[4:5]
	s_add_u32 m0, s13, 0xa400
	ds_read_b128 v[132:135], v205 offset:18432
	v_mfma_f32_16x16x32_bf16 v[56:59], v[176:179], v[156:159], v[56:59]
	global_load_lds_dwordx4 v197, s[4:5]
	ds_read_b128 v[112:115], v204 offset:0
	v_mfma_f32_16x16x32_bf16 v[60:63], v[180:183], v[156:159], v[60:63]
	s_add_u32 s2, s2, 0x80
	s_addc_u32 s3, s3, 0
	ds_read_b128 v[116:119], v204 offset:2048
	v_mfma_f32_16x16x32_bf16 v[32:35], v[184:187], v[160:163], v[32:35]
	s_add_u32 s4, s4, 0x80
	s_addc_u32 s5, s5, 0
	ds_read_b128 v[120:123], v204 offset:4096
	v_mfma_f32_16x16x32_bf16 v[36:39], v[188:191], v[160:163], v[36:39]
	ds_read_b128 v[124:127], v204 offset:6144
	v_mfma_f32_16x16x32_bf16 v[40:43], v[184:187], v[164:167], v[40:43]
	ds_read_b128 v[136:139], v206 offset:16384
	v_mfma_f32_16x16x32_bf16 v[44:47], v[188:191], v[164:167], v[44:47]
	ds_read_b128 v[140:143], v206 offset:18432
	v_mfma_f32_16x16x32_bf16 v[48:51], v[184:187], v[168:171], v[48:51]
	v_mfma_f32_16x16x32_bf16 v[52:55], v[188:191], v[168:171], v[52:55]
	v_mfma_f32_16x16x32_bf16 v[56:59], v[184:187], v[172:175], v[56:59]
	v_mfma_f32_16x16x32_bf16 v[60:63], v[188:191], v[172:175], v[60:63]
	s_waitcnt lgkmcnt(0)
	s_waitcnt vmcnt(0)
	s_barrier
	v_mfma_f32_16x16x32_bf16 v[32:35], v[128:131], v[96:99], v[32:35]
	s_add_u32 m0, s12, 0x0
	ds_read_b128 v[144:147], v203 offset:24576
	v_mfma_f32_16x16x32_bf16 v[36:39], v[132:135], v[96:99], v[36:39]
	global_load_lds_dwordx4 v192, s[8:9]
	s_add_u32 m0, s12, 0x400
	ds_read_b128 v[148:151], v203 offset:26624
	v_mfma_f32_16x16x32_bf16 v[40:43], v[128:131], v[100:103], v[40:43]
	global_load_lds_dwordx4 v193, s[8:9]
	s_add_u32 m0, s12, 0x800
	ds_read_b128 v[152:155], v203 offset:28672
	v_mfma_f32_16x16x32_bf16 v[44:47], v[132:135], v[100:103], v[44:47]
	global_load_lds_dwordx4 v194, s[8:9]
	s_add_u32 m0, s12, 0xc00
	ds_read_b128 v[156:159], v203 offset:30720
	v_mfma_f32_16x16x32_bf16 v[48:51], v[128:131], v[104:107], v[48:51]
	global_load_lds_dwordx4 v195, s[8:9]
	s_add_u32 m0, s13, 0x4000
	ds_read_b128 v[176:179], v205 offset:40960
	v_mfma_f32_16x16x32_bf16 v[52:55], v[132:135], v[104:107], v[52:55]
	global_load_lds_dwordx4 v198, s[10:11]
	s_add_u32 m0, s13, 0x4400
	ds_read_b128 v[180:183], v205 offset:43008
	v_mfma_f32_16x16x32_bf16 v[56:59], v[128:131], v[108:111], v[56:59]
	global_load_lds_dwordx4 v199, s[10:11]
	ds_read_b128 v[160:163], v204 offset:24576
	v_mfma_f32_16x16x32_bf16 v[60:63], v[132:135], v[108:111], v[60:63]
	s_add_u32 s8, s8, 0x80
	s_addc_u32 s9, s9, 0
	ds_read_b128 v[164:167], v204 offset:26624
	v_mfma_f32_16x16x32_bf16 v[32:35], v[136:139], v[112:115], v[32:35]
	s_add_u32 s10, s10, 0x80
	s_addc_u32 s11, s11, 0
	ds_read_b128 v[168:171], v204 offset:28672
	v_mfma_f32_16x16x32_bf16 v[36:39], v[140:143], v[112:115], v[36:39]
	s_sub_u32 s2, s2, 0x800
	s_subb_u32 s3, s3, 0
	ds_read_b128 v[172:175], v204 offset:30720
	v_mfma_f32_16x16x32_bf16 v[40:43], v[136:139], v[116:119], v[40:43]
	s_add_u32 s4, s4, 0x1ff800
	s_addc_u32 s5, s5, 0
	ds_read_b128 v[184:187], v206 offset:40960
	v_mfma_f32_16x16x32_bf16 v[44:47], v[140:143], v[116:119], v[44:47]
	ds_read_b128 v[188:191], v206 offset:43008
	v_mfma_f32_16x16x32_bf16 v[48:51], v[136:139], v[120:123], v[48:51]
	v_mfma_f32_16x16x32_bf16 v[52:55], v[140:143], v[120:123], v[52:55]
	v_mfma_f32_16x16x32_bf16 v[56:59], v[136:139], v[124:127], v[56:59]
	v_mfma_f32_16x16x32_bf16 v[60:63], v[140:143], v[124:127], v[60:63]
	s_waitcnt lgkmcnt(0)
	s_waitcnt vmcnt(0)
	s_barrier
	v_mfma_f32_16x16x32_bf16 v[32:35], v[176:179], v[144:147], v[32:35]
	s_add_u32 m0, s12, 0x6000
	ds_read_b128 v[96:99], v203 offset:0
	v_mfma_f32_16x16x32_bf16 v[36:39], v[180:183], v[144:147], v[36:39]
	global_load_lds_dwordx4 v192, s[8:9]
	s_add_u32 m0, s12, 0x6400
	ds_read_b128 v[100:103], v203 offset:2048
	v_mfma_f32_16x16x32_bf16 v[40:43], v[176:179], v[148:151], v[40:43]
	global_load_lds_dwordx4 v193, s[8:9]
	s_add_u32 m0, s12, 0x6800
	ds_read_b128 v[104:107], v203 offset:4096
	v_mfma_f32_16x16x32_bf16 v[44:47], v[180:183], v[148:151], v[44:47]
	global_load_lds_dwordx4 v194, s[8:9]
	s_add_u32 m0, s12, 0x6c00
	ds_read_b128 v[108:111], v203 offset:6144
	v_mfma_f32_16x16x32_bf16 v[48:51], v[176:179], v[152:155], v[48:51]
	global_load_lds_dwordx4 v195, s[8:9]
	s_add_u32 m0, s13, 0xa000
	ds_read_b128 v[128:131], v205 offset:16384
	v_mfma_f32_16x16x32_bf16 v[52:55], v[180:183], v[152:155], v[52:55]
	global_load_lds_dwordx4 v198, s[10:11]
	s_add_u32 m0, s13, 0xa400
	ds_read_b128 v[132:135], v205 offset:18432
	v_mfma_f32_16x16x32_bf16 v[56:59], v[176:179], v[156:159], v[56:59]
	global_load_lds_dwordx4 v199, s[10:11]
	ds_read_b128 v[112:115], v204 offset:0
	v_mfma_f32_16x16x32_bf16 v[60:63], v[180:183], v[156:159], v[60:63]
	s_add_u32 s8, s8, 0x80
	s_addc_u32 s9, s9, 0
	ds_read_b128 v[116:119], v204 offset:2048
	v_mfma_f32_16x16x32_bf16 v[32:35], v[184:187], v[160:163], v[32:35]
	s_add_u32 s10, s10, 0x80
	s_addc_u32 s11, s11, 0
	ds_read_b128 v[120:123], v204 offset:4096
	v_mfma_f32_16x16x32_bf16 v[36:39], v[188:191], v[160:163], v[36:39]
	ds_read_b128 v[124:127], v204 offset:6144
	v_mfma_f32_16x16x32_bf16 v[40:43], v[184:187], v[164:167], v[40:43]
	ds_read_b128 v[136:139], v206 offset:16384
	v_mfma_f32_16x16x32_bf16 v[44:47], v[188:191], v[164:167], v[44:47]
	ds_read_b128 v[140:143], v206 offset:18432
	v_mfma_f32_16x16x32_bf16 v[48:51], v[184:187], v[168:171], v[48:51]
	v_mfma_f32_16x16x32_bf16 v[52:55], v[188:191], v[168:171], v[52:55]
	v_mfma_f32_16x16x32_bf16 v[56:59], v[184:187], v[172:175], v[56:59]
	v_mfma_f32_16x16x32_bf16 v[60:63], v[188:191], v[172:175], v[60:63]
	s_waitcnt lgkmcnt(0)
	s_nop 7
	s_nop 1
	v_mul_f32_e32 v64, 0xbfb8aa3b, v32
	s_nop 0
	v_exp_f32_e32 v64, v64
	s_nop 0
	v_add_f32_e32 v64, 1.0, v64
	s_nop 0
	v_div_scale_f32 v200, s[14:15], v64, v64, 1.0
	s_nop 0
	v_rcp_f32_e32 v207, v200
	s_nop 0
	v_fma_f32 v208, -v200, v207, 1.0
	s_nop 0
	v_fmac_f32_e32 v207, v208, v207
	s_nop 0
	v_div_scale_f32 v208, vcc, 1.0, v64, 1.0
	s_nop 0
	v_mul_f32_e32 v209, v208, v207
	v_mul_f32_e32 v65, 0xbfb8aa3b, v33
	v_fma_f32 v210, -v200, v209, v208
	v_exp_f32_e32 v65, v65
	v_fmac_f32_e32 v209, v210, v207
	v_add_f32_e32 v65, 1.0, v65
	v_fma_f32 v200, -v200, v209, v208
	v_div_scale_f32 v211, s[14:15], v65, v65, 1.0
	v_div_fmas_f32 v200, v200, v207, v209
	v_rcp_f32_e32 v212, v211
	v_div_fixup_f32 v64, v200, v64, 1.0
	v_fma_f32 v213, -v211, v212, 1.0
	v_bfe_u32 v200, v64, 16, 1
	v_fmac_f32_e32 v212, v213, v212
	v_add3_u32 v64, v64, v200, s69
	v_div_scale_f32 v213, vcc, 1.0, v65, 1.0
	v_and_b32_e32 v64, 0xffff0000, v64
	v_mul_f32_e32 v214, v213, v212
	v_mul_f32_e32 v66, 0xbfb8aa3b, v34
	v_fma_f32 v215, -v211, v214, v213
	v_exp_f32_e32 v66, v66
	v_fmac_f32_e32 v214, v215, v212
	v_add_f32_e32 v66, 1.0, v66
	v_fma_f32 v211, -v211, v214, v213
	v_div_scale_f32 v200, s[14:15], v66, v66, 1.0
	v_div_fmas_f32 v211, v211, v212, v214
	v_rcp_f32_e32 v207, v200
	v_div_fixup_f32 v65, v211, v65, 1.0
	v_fma_f32 v208, -v200, v207, 1.0
	v_bfe_u32 v211, v65, 16, 1
	v_fmac_f32_e32 v207, v208, v207
	v_add3_u32 v65, v65, v211, s69
	v_div_scale_f32 v208, vcc, 1.0, v66, 1.0
	v_and_b32_e32 v65, 0xffff0000, v65
	v_mul_f32_e32 v209, v208, v207
	v_mul_f32_e32 v67, 0xbfb8aa3b, v35
	v_fma_f32 v210, -v200, v209, v208
	v_exp_f32_e32 v67, v67
	v_fmac_f32_e32 v209, v210, v207
	v_add_f32_e32 v67, 1.0, v67
	v_fma_f32 v200, -v200, v209, v208
	v_div_scale_f32 v211, s[14:15], v67, v67, 1.0
	v_div_fmas_f32 v200, v200, v207, v209
	v_rcp_f32_e32 v212, v211
	v_div_fixup_f32 v66, v200, v66, 1.0
	v_fma_f32 v213, -v211, v212, 1.0
	v_bfe_u32 v200, v66, 16, 1
	v_fmac_f32_e32 v212, v213, v212
	v_add3_u32 v66, v66, v200, s69
	v_div_scale_f32 v213, vcc, 1.0, v67, 1.0
	v_and_b32_e32 v66, 0xffff0000, v66
	v_mul_f32_e32 v214, v213, v212
	v_mul_f32_e32 v68, 0xbfb8aa3b, v36
	v_fma_f32 v215, -v211, v214, v213
	v_exp_f32_e32 v68, v68
	v_fmac_f32_e32 v214, v215, v212
	v_add_f32_e32 v68, 1.0, v68
	v_fma_f32 v211, -v211, v214, v213
	v_div_scale_f32 v200, s[14:15], v68, v68, 1.0
	v_div_fmas_f32 v211, v211, v212, v214
	v_rcp_f32_e32 v207, v200
	v_div_fixup_f32 v67, v211, v67, 1.0
	v_fma_f32 v208, -v200, v207, 1.0
	v_bfe_u32 v211, v67, 16, 1
	v_fmac_f32_e32 v207, v208, v207
	v_add3_u32 v67, v67, v211, s69
	v_div_scale_f32 v208, vcc, 1.0, v68, 1.0
	v_and_b32_e32 v67, 0xffff0000, v67
	v_mul_f32_e32 v209, v208, v207
	v_mul_f32_e32 v69, 0xbfb8aa3b, v37
	v_fma_f32 v210, -v200, v209, v208
	v_exp_f32_e32 v69, v69
	v_fmac_f32_e32 v209, v210, v207
	v_add_f32_e32 v69, 1.0, v69
	v_fma_f32 v200, -v200, v209, v208
	v_div_scale_f32 v211, s[14:15], v69, v69, 1.0
	v_div_fmas_f32 v200, v200, v207, v209
	v_rcp_f32_e32 v212, v211
	v_div_fixup_f32 v68, v200, v68, 1.0
	v_fma_f32 v213, -v211, v212, 1.0
	v_bfe_u32 v200, v68, 16, 1
	v_fmac_f32_e32 v212, v213, v212
	v_add3_u32 v68, v68, v200, s69
	v_div_scale_f32 v213, vcc, 1.0, v69, 1.0
	v_and_b32_e32 v68, 0xffff0000, v68
	v_mul_f32_e32 v214, v213, v212
	v_mul_f32_e32 v70, 0xbfb8aa3b, v38
	v_fma_f32 v215, -v211, v214, v213
	v_exp_f32_e32 v70, v70
	v_fmac_f32_e32 v214, v215, v212
	v_add_f32_e32 v70, 1.0, v70
	v_fma_f32 v211, -v211, v214, v213
	v_div_scale_f32 v200, s[14:15], v70, v70, 1.0
	v_div_fmas_f32 v211, v211, v212, v214
	v_rcp_f32_e32 v207, v200
	v_div_fixup_f32 v69, v211, v69, 1.0
	v_fma_f32 v208, -v200, v207, 1.0
	v_bfe_u32 v211, v69, 16, 1
	v_fmac_f32_e32 v207, v208, v207
	v_add3_u32 v69, v69, v211, s69
	v_div_scale_f32 v208, vcc, 1.0, v70, 1.0
	v_and_b32_e32 v69, 0xffff0000, v69
	v_mul_f32_e32 v209, v208, v207
	v_mul_f32_e32 v71, 0xbfb8aa3b, v39
	v_fma_f32 v210, -v200, v209, v208
	v_exp_f32_e32 v71, v71
	v_fmac_f32_e32 v209, v210, v207
	v_add_f32_e32 v71, 1.0, v71
	v_fma_f32 v200, -v200, v209, v208
	v_div_scale_f32 v211, s[14:15], v71, v71, 1.0
	v_div_fmas_f32 v200, v200, v207, v209
	v_rcp_f32_e32 v212, v211
	v_div_fixup_f32 v70, v200, v70, 1.0
	v_fma_f32 v213, -v211, v212, 1.0
	v_bfe_u32 v200, v70, 16, 1
	v_fmac_f32_e32 v212, v213, v212
	v_add3_u32 v70, v70, v200, s69
	v_div_scale_f32 v213, vcc, 1.0, v71, 1.0
	v_and_b32_e32 v70, 0xffff0000, v70
	v_mul_f32_e32 v214, v213, v212
	v_mul_f32_e32 v72, 0xbfb8aa3b, v40
	v_fma_f32 v215, -v211, v214, v213
	v_exp_f32_e32 v72, v72
	v_fmac_f32_e32 v214, v215, v212
	v_add_f32_e32 v72, 1.0, v72
	v_fma_f32 v211, -v211, v214, v213
	v_div_scale_f32 v200, s[14:15], v72, v72, 1.0
	v_div_fmas_f32 v211, v211, v212, v214
	v_rcp_f32_e32 v207, v200
	v_div_fixup_f32 v71, v211, v71, 1.0
	v_fma_f32 v208, -v200, v207, 1.0
	v_bfe_u32 v211, v71, 16, 1
	v_fmac_f32_e32 v207, v208, v207
	v_add3_u32 v71, v71, v211, s69
	v_div_scale_f32 v208, vcc, 1.0, v72, 1.0
	v_and_b32_e32 v71, 0xffff0000, v71
	v_mul_f32_e32 v209, v208, v207
	v_mul_f32_e32 v73, 0xbfb8aa3b, v41
	v_fma_f32 v210, -v200, v209, v208
	v_exp_f32_e32 v73, v73
	v_fmac_f32_e32 v209, v210, v207
	v_add_f32_e32 v73, 1.0, v73
	v_fma_f32 v200, -v200, v209, v208
	v_div_scale_f32 v211, s[14:15], v73, v73, 1.0
	v_div_fmas_f32 v200, v200, v207, v209
	v_rcp_f32_e32 v212, v211
	v_div_fixup_f32 v72, v200, v72, 1.0
	v_fma_f32 v213, -v211, v212, 1.0
	v_bfe_u32 v200, v72, 16, 1
	v_fmac_f32_e32 v212, v213, v212
	v_add3_u32 v72, v72, v200, s69
	v_div_scale_f32 v213, vcc, 1.0, v73, 1.0
	v_and_b32_e32 v72, 0xffff0000, v72
	v_mul_f32_e32 v214, v213, v212
	v_mul_f32_e32 v74, 0xbfb8aa3b, v42
	v_fma_f32 v215, -v211, v214, v213
	v_exp_f32_e32 v74, v74
	v_fmac_f32_e32 v214, v215, v212
	v_add_f32_e32 v74, 1.0, v74
	v_fma_f32 v211, -v211, v214, v213
	v_div_scale_f32 v200, s[14:15], v74, v74, 1.0
	v_div_fmas_f32 v211, v211, v212, v214
	v_rcp_f32_e32 v207, v200
	v_div_fixup_f32 v73, v211, v73, 1.0
	v_fma_f32 v208, -v200, v207, 1.0
	v_bfe_u32 v211, v73, 16, 1
	v_fmac_f32_e32 v207, v208, v207
	v_add3_u32 v73, v73, v211, s69
	v_div_scale_f32 v208, vcc, 1.0, v74, 1.0
	v_and_b32_e32 v73, 0xffff0000, v73
	v_mul_f32_e32 v209, v208, v207
	v_mul_f32_e32 v75, 0xbfb8aa3b, v43
	v_fma_f32 v210, -v200, v209, v208
	v_exp_f32_e32 v75, v75
	v_fmac_f32_e32 v209, v210, v207
	v_add_f32_e32 v75, 1.0, v75
	v_fma_f32 v200, -v200, v209, v208
	v_div_scale_f32 v211, s[14:15], v75, v75, 1.0
	v_div_fmas_f32 v200, v200, v207, v209
	v_rcp_f32_e32 v212, v211
	v_div_fixup_f32 v74, v200, v74, 1.0
	v_fma_f32 v213, -v211, v212, 1.0
	v_bfe_u32 v200, v74, 16, 1
	v_fmac_f32_e32 v212, v213, v212
	v_add3_u32 v74, v74, v200, s69
	v_div_scale_f32 v213, vcc, 1.0, v75, 1.0
	v_and_b32_e32 v74, 0xffff0000, v74
	v_mul_f32_e32 v214, v213, v212
	v_mul_f32_e32 v76, 0xbfb8aa3b, v44
	v_fma_f32 v215, -v211, v214, v213
	v_exp_f32_e32 v76, v76
	v_fmac_f32_e32 v214, v215, v212
	v_add_f32_e32 v76, 1.0, v76
	v_fma_f32 v211, -v211, v214, v213
	v_div_scale_f32 v200, s[14:15], v76, v76, 1.0
	v_div_fmas_f32 v211, v211, v212, v214
	v_rcp_f32_e32 v207, v200
	v_div_fixup_f32 v75, v211, v75, 1.0
	v_fma_f32 v208, -v200, v207, 1.0
	v_bfe_u32 v211, v75, 16, 1
	v_fmac_f32_e32 v207, v208, v207
	v_add3_u32 v75, v75, v211, s69
	v_div_scale_f32 v208, vcc, 1.0, v76, 1.0
	v_and_b32_e32 v75, 0xffff0000, v75
	v_mul_f32_e32 v209, v208, v207
	v_mul_f32_e32 v77, 0xbfb8aa3b, v45
	v_fma_f32 v210, -v200, v209, v208
	v_exp_f32_e32 v77, v77
	v_fmac_f32_e32 v209, v210, v207
	v_add_f32_e32 v77, 1.0, v77
	v_fma_f32 v200, -v200, v209, v208
	v_div_scale_f32 v211, s[14:15], v77, v77, 1.0
	v_div_fmas_f32 v200, v200, v207, v209
	v_rcp_f32_e32 v212, v211
	v_div_fixup_f32 v76, v200, v76, 1.0
	v_fma_f32 v213, -v211, v212, 1.0
	v_bfe_u32 v200, v76, 16, 1
	v_fmac_f32_e32 v212, v213, v212
	v_add3_u32 v76, v76, v200, s69
	v_div_scale_f32 v213, vcc, 1.0, v77, 1.0
	v_and_b32_e32 v76, 0xffff0000, v76
	v_mul_f32_e32 v214, v213, v212
	v_mul_f32_e32 v78, 0xbfb8aa3b, v46
	v_fma_f32 v215, -v211, v214, v213
	v_exp_f32_e32 v78, v78
	v_fmac_f32_e32 v214, v215, v212
	v_add_f32_e32 v78, 1.0, v78
	v_fma_f32 v211, -v211, v214, v213
	v_div_scale_f32 v200, s[14:15], v78, v78, 1.0
	v_div_fmas_f32 v211, v211, v212, v214
	v_rcp_f32_e32 v207, v200
	v_div_fixup_f32 v77, v211, v77, 1.0
	v_fma_f32 v208, -v200, v207, 1.0
	v_bfe_u32 v211, v77, 16, 1
	v_fmac_f32_e32 v207, v208, v207
	v_add3_u32 v77, v77, v211, s69
	v_div_scale_f32 v208, vcc, 1.0, v78, 1.0
	v_and_b32_e32 v77, 0xffff0000, v77
	v_mul_f32_e32 v209, v208, v207
	v_mul_f32_e32 v79, 0xbfb8aa3b, v47
	v_fma_f32 v210, -v200, v209, v208
	v_exp_f32_e32 v79, v79
	v_fmac_f32_e32 v209, v210, v207
	v_add_f32_e32 v79, 1.0, v79
	v_fma_f32 v200, -v200, v209, v208
	v_div_scale_f32 v211, s[14:15], v79, v79, 1.0
	v_div_fmas_f32 v200, v200, v207, v209
	v_rcp_f32_e32 v212, v211
	v_div_fixup_f32 v78, v200, v78, 1.0
	v_fma_f32 v213, -v211, v212, 1.0
	v_bfe_u32 v200, v78, 16, 1
	v_fmac_f32_e32 v212, v213, v212
	v_add3_u32 v78, v78, v200, s69
	v_div_scale_f32 v213, vcc, 1.0, v79, 1.0
	v_and_b32_e32 v78, 0xffff0000, v78
	v_mul_f32_e32 v214, v213, v212
	v_mul_f32_e32 v80, 0xbfb8aa3b, v48
	v_fma_f32 v215, -v211, v214, v213
	v_exp_f32_e32 v80, v80
	v_fmac_f32_e32 v214, v215, v212
	v_add_f32_e32 v80, 1.0, v80
	v_fma_f32 v211, -v211, v214, v213
	v_div_scale_f32 v200, s[14:15], v80, v80, 1.0
	v_div_fmas_f32 v211, v211, v212, v214
	v_rcp_f32_e32 v207, v200
	v_div_fixup_f32 v79, v211, v79, 1.0
	v_fma_f32 v208, -v200, v207, 1.0
	v_bfe_u32 v211, v79, 16, 1
	v_fmac_f32_e32 v207, v208, v207
	v_add3_u32 v79, v79, v211, s69
	v_div_scale_f32 v208, vcc, 1.0, v80, 1.0
	v_and_b32_e32 v79, 0xffff0000, v79
	v_mul_f32_e32 v209, v208, v207
	v_mul_f32_e32 v81, 0xbfb8aa3b, v49
	v_fma_f32 v210, -v200, v209, v208
	v_exp_f32_e32 v81, v81
	v_fmac_f32_e32 v209, v210, v207
	v_add_f32_e32 v81, 1.0, v81
	v_fma_f32 v200, -v200, v209, v208
	v_div_scale_f32 v211, s[14:15], v81, v81, 1.0
	v_div_fmas_f32 v200, v200, v207, v209
	v_rcp_f32_e32 v212, v211
	v_div_fixup_f32 v80, v200, v80, 1.0
	v_fma_f32 v213, -v211, v212, 1.0
	v_bfe_u32 v200, v80, 16, 1
	v_fmac_f32_e32 v212, v213, v212
	v_add3_u32 v80, v80, v200, s69
	v_div_scale_f32 v213, vcc, 1.0, v81, 1.0
	v_and_b32_e32 v80, 0xffff0000, v80
	v_mul_f32_e32 v214, v213, v212
	v_mul_f32_e32 v82, 0xbfb8aa3b, v50
	v_fma_f32 v215, -v211, v214, v213
	v_exp_f32_e32 v82, v82
	v_fmac_f32_e32 v214, v215, v212
	v_add_f32_e32 v82, 1.0, v82
	v_fma_f32 v211, -v211, v214, v213
	v_div_scale_f32 v200, s[14:15], v82, v82, 1.0
	v_div_fmas_f32 v211, v211, v212, v214
	v_rcp_f32_e32 v207, v200
	v_div_fixup_f32 v81, v211, v81, 1.0
	v_fma_f32 v208, -v200, v207, 1.0
	v_bfe_u32 v211, v81, 16, 1
	v_fmac_f32_e32 v207, v208, v207
	v_add3_u32 v81, v81, v211, s69
	v_div_scale_f32 v208, vcc, 1.0, v82, 1.0
	v_and_b32_e32 v81, 0xffff0000, v81
	v_mul_f32_e32 v209, v208, v207
	v_mul_f32_e32 v83, 0xbfb8aa3b, v51
	v_fma_f32 v210, -v200, v209, v208
	v_exp_f32_e32 v83, v83
	v_fmac_f32_e32 v209, v210, v207
	v_add_f32_e32 v83, 1.0, v83
	v_fma_f32 v200, -v200, v209, v208
	v_div_scale_f32 v211, s[14:15], v83, v83, 1.0
	v_div_fmas_f32 v200, v200, v207, v209
	v_rcp_f32_e32 v212, v211
	v_div_fixup_f32 v82, v200, v82, 1.0
	v_fma_f32 v213, -v211, v212, 1.0
	v_bfe_u32 v200, v82, 16, 1
	v_fmac_f32_e32 v212, v213, v212
	v_add3_u32 v82, v82, v200, s69
	v_div_scale_f32 v213, vcc, 1.0, v83, 1.0
	v_and_b32_e32 v82, 0xffff0000, v82
	v_mul_f32_e32 v214, v213, v212
	v_mul_f32_e32 v84, 0xbfb8aa3b, v52
	v_fma_f32 v215, -v211, v214, v213
	v_exp_f32_e32 v84, v84
	v_fmac_f32_e32 v214, v215, v212
	v_add_f32_e32 v84, 1.0, v84
	v_fma_f32 v211, -v211, v214, v213
	v_div_scale_f32 v200, s[14:15], v84, v84, 1.0
	v_div_fmas_f32 v211, v211, v212, v214
	v_rcp_f32_e32 v207, v200
	v_div_fixup_f32 v83, v211, v83, 1.0
	v_fma_f32 v208, -v200, v207, 1.0
	v_bfe_u32 v211, v83, 16, 1
	v_fmac_f32_e32 v207, v208, v207
	v_add3_u32 v83, v83, v211, s69
	v_div_scale_f32 v208, vcc, 1.0, v84, 1.0
	v_and_b32_e32 v83, 0xffff0000, v83
	v_mul_f32_e32 v209, v208, v207
	v_mul_f32_e32 v85, 0xbfb8aa3b, v53
	v_fma_f32 v210, -v200, v209, v208
	v_exp_f32_e32 v85, v85
	v_fmac_f32_e32 v209, v210, v207
	v_add_f32_e32 v85, 1.0, v85
	v_fma_f32 v200, -v200, v209, v208
	v_div_scale_f32 v211, s[14:15], v85, v85, 1.0
	v_div_fmas_f32 v200, v200, v207, v209
	v_rcp_f32_e32 v212, v211
	v_div_fixup_f32 v84, v200, v84, 1.0
	v_fma_f32 v213, -v211, v212, 1.0
	v_bfe_u32 v200, v84, 16, 1
	v_fmac_f32_e32 v212, v213, v212
	v_add3_u32 v84, v84, v200, s69
	v_div_scale_f32 v213, vcc, 1.0, v85, 1.0
	v_and_b32_e32 v84, 0xffff0000, v84
	v_mul_f32_e32 v214, v213, v212
	v_mul_f32_e32 v86, 0xbfb8aa3b, v54
	v_fma_f32 v215, -v211, v214, v213
	v_exp_f32_e32 v86, v86
	v_fmac_f32_e32 v214, v215, v212
	v_add_f32_e32 v86, 1.0, v86
	v_fma_f32 v211, -v211, v214, v213
	v_div_scale_f32 v200, s[14:15], v86, v86, 1.0
	v_div_fmas_f32 v211, v211, v212, v214
	v_rcp_f32_e32 v207, v200
	v_div_fixup_f32 v85, v211, v85, 1.0
	v_fma_f32 v208, -v200, v207, 1.0
	v_bfe_u32 v211, v85, 16, 1
	v_fmac_f32_e32 v207, v208, v207
	v_add3_u32 v85, v85, v211, s69
	v_div_scale_f32 v208, vcc, 1.0, v86, 1.0
	v_and_b32_e32 v85, 0xffff0000, v85
	v_mul_f32_e32 v209, v208, v207
	v_mul_f32_e32 v87, 0xbfb8aa3b, v55
	v_fma_f32 v210, -v200, v209, v208
	v_exp_f32_e32 v87, v87
	v_fmac_f32_e32 v209, v210, v207
	v_add_f32_e32 v87, 1.0, v87
	v_fma_f32 v200, -v200, v209, v208
	v_div_scale_f32 v211, s[14:15], v87, v87, 1.0
	v_div_fmas_f32 v200, v200, v207, v209
	v_rcp_f32_e32 v212, v211
	v_div_fixup_f32 v86, v200, v86, 1.0
	v_fma_f32 v213, -v211, v212, 1.0
	v_bfe_u32 v200, v86, 16, 1
	v_fmac_f32_e32 v212, v213, v212
	v_add3_u32 v86, v86, v200, s69
	v_div_scale_f32 v213, vcc, 1.0, v87, 1.0
	v_and_b32_e32 v86, 0xffff0000, v86
	v_mul_f32_e32 v214, v213, v212
	v_mul_f32_e32 v88, 0xbfb8aa3b, v56
	v_fma_f32 v215, -v211, v214, v213
	v_exp_f32_e32 v88, v88
	v_fmac_f32_e32 v214, v215, v212
	v_add_f32_e32 v88, 1.0, v88
	v_fma_f32 v211, -v211, v214, v213
	v_div_scale_f32 v200, s[14:15], v88, v88, 1.0
	v_div_fmas_f32 v211, v211, v212, v214
	v_rcp_f32_e32 v207, v200
	v_div_fixup_f32 v87, v211, v87, 1.0
	v_fma_f32 v208, -v200, v207, 1.0
	v_bfe_u32 v211, v87, 16, 1
	v_fmac_f32_e32 v207, v208, v207
	v_add3_u32 v87, v87, v211, s69
	v_div_scale_f32 v208, vcc, 1.0, v88, 1.0
	v_and_b32_e32 v87, 0xffff0000, v87
	v_mul_f32_e32 v209, v208, v207
	v_mul_f32_e32 v89, 0xbfb8aa3b, v57
	v_fma_f32 v210, -v200, v209, v208
	v_exp_f32_e32 v89, v89
	v_fmac_f32_e32 v209, v210, v207
	v_add_f32_e32 v89, 1.0, v89
	v_fma_f32 v200, -v200, v209, v208
	v_div_scale_f32 v211, s[14:15], v89, v89, 1.0
	v_div_fmas_f32 v200, v200, v207, v209
	v_rcp_f32_e32 v212, v211
	v_div_fixup_f32 v88, v200, v88, 1.0
	v_fma_f32 v213, -v211, v212, 1.0
	v_bfe_u32 v200, v88, 16, 1
	v_fmac_f32_e32 v212, v213, v212
	v_add3_u32 v88, v88, v200, s69
	v_div_scale_f32 v213, vcc, 1.0, v89, 1.0
	v_and_b32_e32 v88, 0xffff0000, v88
	v_mul_f32_e32 v214, v213, v212
	v_mul_f32_e32 v90, 0xbfb8aa3b, v58
	v_fma_f32 v215, -v211, v214, v213
	v_exp_f32_e32 v90, v90
	v_fmac_f32_e32 v214, v215, v212
	v_add_f32_e32 v90, 1.0, v90
	v_fma_f32 v211, -v211, v214, v213
	v_div_scale_f32 v200, s[14:15], v90, v90, 1.0
	v_div_fmas_f32 v211, v211, v212, v214
	v_rcp_f32_e32 v207, v200
	v_div_fixup_f32 v89, v211, v89, 1.0
	v_fma_f32 v208, -v200, v207, 1.0
	v_bfe_u32 v211, v89, 16, 1
	v_fmac_f32_e32 v207, v208, v207
	v_add3_u32 v89, v89, v211, s69
	v_div_scale_f32 v208, vcc, 1.0, v90, 1.0
	v_and_b32_e32 v89, 0xffff0000, v89
	v_mul_f32_e32 v209, v208, v207
	v_mul_f32_e32 v91, 0xbfb8aa3b, v59
	v_fma_f32 v210, -v200, v209, v208
	v_exp_f32_e32 v91, v91
	v_fmac_f32_e32 v209, v210, v207
	v_add_f32_e32 v91, 1.0, v91
	v_fma_f32 v200, -v200, v209, v208
	v_div_scale_f32 v211, s[14:15], v91, v91, 1.0
	v_div_fmas_f32 v200, v200, v207, v209
	v_rcp_f32_e32 v212, v211
	v_div_fixup_f32 v90, v200, v90, 1.0
	v_fma_f32 v213, -v211, v212, 1.0
	v_bfe_u32 v200, v90, 16, 1
	v_fmac_f32_e32 v212, v213, v212
	v_add3_u32 v90, v90, v200, s69
	v_div_scale_f32 v213, vcc, 1.0, v91, 1.0
	v_and_b32_e32 v90, 0xffff0000, v90
	v_mul_f32_e32 v214, v213, v212
	v_mul_f32_e32 v92, 0xbfb8aa3b, v60
	v_fma_f32 v215, -v211, v214, v213
	v_exp_f32_e32 v92, v92
	v_fmac_f32_e32 v214, v215, v212
	v_add_f32_e32 v92, 1.0, v92
	v_fma_f32 v211, -v211, v214, v213
	v_div_scale_f32 v200, s[14:15], v92, v92, 1.0
	v_div_fmas_f32 v211, v211, v212, v214
	v_rcp_f32_e32 v207, v200
	v_div_fixup_f32 v91, v211, v91, 1.0
	v_fma_f32 v208, -v200, v207, 1.0
	v_bfe_u32 v211, v91, 16, 1
	v_fmac_f32_e32 v207, v208, v207
	v_add3_u32 v91, v91, v211, s69
	v_div_scale_f32 v208, vcc, 1.0, v92, 1.0
	v_and_b32_e32 v91, 0xffff0000, v91
	v_mul_f32_e32 v209, v208, v207
	v_mul_f32_e32 v93, 0xbfb8aa3b, v61
	v_fma_f32 v210, -v200, v209, v208
	v_exp_f32_e32 v93, v93
	v_fmac_f32_e32 v209, v210, v207
	v_add_f32_e32 v93, 1.0, v93
	v_fma_f32 v200, -v200, v209, v208
	v_div_scale_f32 v211, s[14:15], v93, v93, 1.0
	v_div_fmas_f32 v200, v200, v207, v209
	v_rcp_f32_e32 v212, v211
	v_div_fixup_f32 v92, v200, v92, 1.0
	v_fma_f32 v213, -v211, v212, 1.0
	v_bfe_u32 v200, v92, 16, 1
	v_fmac_f32_e32 v212, v213, v212
	v_add3_u32 v92, v92, v200, s69
	v_div_scale_f32 v213, vcc, 1.0, v93, 1.0
	v_and_b32_e32 v92, 0xffff0000, v92
	v_mul_f32_e32 v214, v213, v212
	v_mul_f32_e32 v94, 0xbfb8aa3b, v62
	v_fma_f32 v215, -v211, v214, v213
	v_exp_f32_e32 v94, v94
	v_fmac_f32_e32 v214, v215, v212
	v_add_f32_e32 v94, 1.0, v94
	v_fma_f32 v211, -v211, v214, v213
	v_div_scale_f32 v200, s[14:15], v94, v94, 1.0
	v_div_fmas_f32 v211, v211, v212, v214
	v_rcp_f32_e32 v207, v200
	v_div_fixup_f32 v93, v211, v93, 1.0
	v_fma_f32 v208, -v200, v207, 1.0
	v_bfe_u32 v211, v93, 16, 1
	v_fmac_f32_e32 v207, v208, v207
	v_add3_u32 v93, v93, v211, s69
	v_div_scale_f32 v208, vcc, 1.0, v94, 1.0
	v_and_b32_e32 v93, 0xffff0000, v93
	v_mul_f32_e32 v209, v208, v207
	v_mul_f32_e32 v95, 0xbfb8aa3b, v63
	v_fma_f32 v210, -v200, v209, v208
	v_exp_f32_e32 v95, v95
	v_fmac_f32_e32 v209, v210, v207
	v_add_f32_e32 v95, 1.0, v95
	v_fma_f32 v200, -v200, v209, v208
	v_div_scale_f32 v211, s[14:15], v95, v95, 1.0
	v_div_fmas_f32 v200, v200, v207, v209
	v_rcp_f32_e32 v212, v211
	v_div_fixup_f32 v94, v200, v94, 1.0
	v_fma_f32 v213, -v211, v212, 1.0
	v_bfe_u32 v200, v94, 16, 1
	v_fmac_f32_e32 v212, v213, v212
	v_add3_u32 v94, v94, v200, s69
	v_div_scale_f32 v213, vcc, 1.0, v95, 1.0
	v_and_b32_e32 v94, 0xffff0000, v94
	v_mul_f32_e32 v214, v213, v212
	v_fma_f32 v215, -v211, v214, v213
	s_nop 0
	v_fmac_f32_e32 v214, v215, v212
	s_nop 0
	v_fma_f32 v211, -v211, v214, v213
	s_nop 0
	v_div_fmas_f32 v211, v211, v212, v214
	s_nop 0
	v_div_fixup_f32 v95, v211, v95, 1.0
	s_nop 0
	v_bfe_u32 v211, v95, 16, 1
	s_nop 0
	v_add3_u32 v95, v95, v211, s69
	s_nop 0
	v_and_b32_e32 v95, 0xffff0000, v95
	s_nop 0
	v_mov_b32_e32 v32, 0
	v_mov_b32_e32 v33, 0
	v_mov_b32_e32 v34, 0
	v_mov_b32_e32 v35, 0
	v_mov_b32_e32 v36, 0
	v_mov_b32_e32 v37, 0
	v_mov_b32_e32 v38, 0
	v_mov_b32_e32 v39, 0
	v_mov_b32_e32 v40, 0
	v_mov_b32_e32 v41, 0
	v_mov_b32_e32 v42, 0
	v_mov_b32_e32 v43, 0
	v_mov_b32_e32 v44, 0
	v_mov_b32_e32 v45, 0
	v_mov_b32_e32 v46, 0
	v_mov_b32_e32 v47, 0
	v_mov_b32_e32 v48, 0
	v_mov_b32_e32 v49, 0
	v_mov_b32_e32 v50, 0
	v_mov_b32_e32 v51, 0
	v_mov_b32_e32 v52, 0
	v_mov_b32_e32 v53, 0
	v_mov_b32_e32 v54, 0
	v_mov_b32_e32 v55, 0
	v_mov_b32_e32 v56, 0
	v_mov_b32_e32 v57, 0
	v_mov_b32_e32 v58, 0
	v_mov_b32_e32 v59, 0
	v_mov_b32_e32 v60, 0
	v_mov_b32_e32 v61, 0
	v_mov_b32_e32 v62, 0
	v_mov_b32_e32 v63, 0
	s_waitcnt vmcnt(0)
	s_barrier
	v_mfma_f32_16x16x32_bf16 v[32:35], v[128:131], v[96:99], v[32:35]
	s_add_u32 m0, s12, 0x0
	ds_read_b128 v[144:147], v203 offset:24576
	v_mfma_f32_16x16x32_bf16 v[36:39], v[132:135], v[96:99], v[36:39]
	global_load_lds_dwordx4 v192, s[8:9]
	s_add_u32 m0, s12, 0x400
	ds_read_b128 v[148:151], v203 offset:26624
	v_mfma_f32_16x16x32_bf16 v[40:43], v[128:131], v[100:103], v[40:43]
	global_load_lds_dwordx4 v193, s[8:9]
	s_add_u32 m0, s12, 0x800
	ds_read_b128 v[152:155], v203 offset:28672
	v_mfma_f32_16x16x32_bf16 v[44:47], v[132:135], v[100:103], v[44:47]
	global_load_lds_dwordx4 v194, s[8:9]
	s_add_u32 m0, s12, 0xc00
	ds_read_b128 v[156:159], v203 offset:30720
	v_mfma_f32_16x16x32_bf16 v[48:51], v[128:131], v[104:107], v[48:51]
	global_load_lds_dwordx4 v195, s[8:9]
	s_add_u32 m0, s13, 0x4000
	ds_read_b128 v[176:179], v205 offset:40960
	v_mfma_f32_16x16x32_bf16 v[52:55], v[132:135], v[104:107], v[52:55]
	global_load_lds_dwordx4 v198, s[10:11]
	s_add_u32 m0, s13, 0x4400
	ds_read_b128 v[180:183], v205 offset:43008
	v_mfma_f32_16x16x32_bf16 v[56:59], v[128:131], v[108:111], v[56:59]
	global_load_lds_dwordx4 v199, s[10:11]
	ds_read_b128 v[160:163], v204 offset:24576
	v_mfma_f32_16x16x32_bf16 v[60:63], v[132:135], v[108:111], v[60:63]
	s_add_u32 s8, s8, 0x80
	s_addc_u32 s9, s9, 0
	ds_read_b128 v[164:167], v204 offset:26624
	v_mfma_f32_16x16x32_bf16 v[32:35], v[136:139], v[112:115], v[32:35]
	s_add_u32 s10, s10, 0x80
	s_addc_u32 s11, s11, 0
	ds_read_b128 v[168:171], v204 offset:28672
	v_mfma_f32_16x16x32_bf16 v[36:39], v[140:143], v[112:115], v[36:39]
	ds_read_b128 v[172:175], v204 offset:30720
	v_mfma_f32_16x16x32_bf16 v[40:43], v[136:139], v[116:119], v[40:43]
	ds_read_b128 v[184:187], v206 offset:40960
	v_mfma_f32_16x16x32_bf16 v[44:47], v[140:143], v[116:119], v[44:47]
	ds_read_b128 v[188:191], v206 offset:43008
	v_mfma_f32_16x16x32_bf16 v[48:51], v[136:139], v[120:123], v[48:51]
	v_mfma_f32_16x16x32_bf16 v[52:55], v[140:143], v[120:123], v[52:55]
	v_mfma_f32_16x16x32_bf16 v[56:59], v[136:139], v[124:127], v[56:59]
	v_mfma_f32_16x16x32_bf16 v[60:63], v[140:143], v[124:127], v[60:63]
	s_waitcnt lgkmcnt(0)
	s_waitcnt vmcnt(0)
	s_barrier
	v_mfma_f32_16x16x32_bf16 v[32:35], v[176:179], v[144:147], v[32:35]
	s_add_u32 m0, s12, 0x6000
	ds_read_b128 v[96:99], v203 offset:0
	v_mfma_f32_16x16x32_bf16 v[36:39], v[180:183], v[144:147], v[36:39]
	global_load_lds_dwordx4 v192, s[8:9]
	s_add_u32 m0, s12, 0x6400
	ds_read_b128 v[100:103], v203 offset:2048
	v_mfma_f32_16x16x32_bf16 v[40:43], v[176:179], v[148:151], v[40:43]
	global_load_lds_dwordx4 v193, s[8:9]
	s_add_u32 m0, s12, 0x6800
	ds_read_b128 v[104:107], v203 offset:4096
	v_mfma_f32_16x16x32_bf16 v[44:47], v[180:183], v[148:151], v[44:47]
	global_load_lds_dwordx4 v194, s[8:9]
	s_add_u32 m0, s12, 0x6c00
	ds_read_b128 v[108:111], v203 offset:6144
	v_mfma_f32_16x16x32_bf16 v[48:51], v[176:179], v[152:155], v[48:51]
	global_load_lds_dwordx4 v195, s[8:9]
	s_add_u32 m0, s13, 0xa000
	ds_read_b128 v[128:131], v205 offset:16384
	v_mfma_f32_16x16x32_bf16 v[52:55], v[180:183], v[152:155], v[52:55]
	global_load_lds_dwordx4 v198, s[10:11]
	s_add_u32 m0, s13, 0xa400
	ds_read_b128 v[132:135], v205 offset:18432
	v_mfma_f32_16x16x32_bf16 v[56:59], v[176:179], v[156:159], v[56:59]
	global_load_lds_dwordx4 v199, s[10:11]
	ds_read_b128 v[112:115], v204 offset:0
	v_mfma_f32_16x16x32_bf16 v[60:63], v[180:183], v[156:159], v[60:63]
	s_add_u32 s8, s8, 0x80
	s_addc_u32 s9, s9, 0
	ds_read_b128 v[116:119], v204 offset:2048
	v_mfma_f32_16x16x32_bf16 v[32:35], v[184:187], v[160:163], v[32:35]
	s_add_u32 s10, s10, 0x80
	s_addc_u32 s11, s11, 0
	ds_read_b128 v[120:123], v204 offset:4096
	v_mfma_f32_16x16x32_bf16 v[36:39], v[188:191], v[160:163], v[36:39]
	s_add_u32 s10, s10, 0x7fe00
	s_addc_u32 s11, s11, 0
	ds_read_b128 v[124:127], v204 offset:6144
	v_mfma_f32_16x16x32_bf16 v[40:43], v[184:187], v[164:167], v[40:43]
	ds_read_b128 v[136:139], v206 offset:16384
	v_mfma_f32_16x16x32_bf16 v[44:47], v[188:191], v[164:167], v[44:47]
	ds_read_b128 v[140:143], v206 offset:18432
	v_mfma_f32_16x16x32_bf16 v[48:51], v[184:187], v[168:171], v[48:51]
	v_mfma_f32_16x16x32_bf16 v[52:55], v[188:191], v[168:171], v[52:55]
	v_mfma_f32_16x16x32_bf16 v[56:59], v[184:187], v[172:175], v[56:59]
	v_mfma_f32_16x16x32_bf16 v[60:63], v[188:191], v[172:175], v[60:63]
	s_waitcnt lgkmcnt(0)
	s_cmp_eq_u32 s17, 3
	s_cbranch_scc1 .Lg4_last
	s_waitcnt vmcnt(0)
	s_barrier
	v_mfma_f32_16x16x32_bf16 v[32:35], v[128:131], v[96:99], v[32:35]
	s_add_u32 m0, s12, 0x0
	ds_read_b128 v[144:147], v203 offset:24576
	v_mfma_f32_16x16x32_bf16 v[36:39], v[132:135], v[96:99], v[36:39]
	global_load_lds_dwordx4 v192, s[2:3]
	s_add_u32 m0, s12, 0x400
	ds_read_b128 v[148:151], v203 offset:26624
	v_mfma_f32_16x16x32_bf16 v[40:43], v[128:131], v[100:103], v[40:43]
	global_load_lds_dwordx4 v193, s[2:3]
	s_add_u32 m0, s12, 0x800
	ds_read_b128 v[152:155], v203 offset:28672
	v_mfma_f32_16x16x32_bf16 v[44:47], v[132:135], v[100:103], v[44:47]
	global_load_lds_dwordx4 v194, s[2:3]
	s_add_u32 m0, s12, 0xc00
	ds_read_b128 v[156:159], v203 offset:30720
	v_mfma_f32_16x16x32_bf16 v[48:51], v[128:131], v[104:107], v[48:51]
	global_load_lds_dwordx4 v195, s[2:3]
	s_add_u32 m0, s13, 0x4000
	ds_read_b128 v[176:179], v205 offset:40960
	v_mfma_f32_16x16x32_bf16 v[52:55], v[132:135], v[104:107], v[52:55]
	global_load_lds_dwordx4 v196, s[4:5]
	s_add_u32 m0, s13, 0x4400
	ds_read_b128 v[180:183], v205 offset:43008
	v_mfma_f32_16x16x32_bf16 v[56:59], v[128:131], v[108:111], v[56:59]
	global_load_lds_dwordx4 v197, s[4:5]
	ds_read_b128 v[160:163], v204 offset:24576
	v_mfma_f32_16x16x32_bf16 v[60:63], v[132:135], v[108:111], v[60:63]
	s_add_u32 s2, s2, 0x80
	s_addc_u32 s3, s3, 0
	ds_read_b128 v[164:167], v204 offset:26624
	v_mfma_f32_16x16x32_bf16 v[32:35], v[136:139], v[112:115], v[32:35]
	s_add_u32 s4, s4, 0x80
	s_addc_u32 s5, s5, 0
	ds_read_b128 v[168:171], v204 offset:28672
	v_mfma_f32_16x16x32_bf16 v[36:39], v[140:143], v[112:115], v[36:39]
	ds_read_b128 v[172:175], v204 offset:30720
	v_mfma_f32_16x16x32_bf16 v[40:43], v[136:139], v[116:119], v[40:43]
	ds_read_b128 v[184:187], v206 offset:40960
	v_mfma_f32_16x16x32_bf16 v[44:47], v[140:143], v[116:119], v[44:47]
	ds_read_b128 v[188:191], v206 offset:43008
	v_mfma_f32_16x16x32_bf16 v[48:51], v[136:139], v[120:123], v[48:51]
	v_mfma_f32_16x16x32_bf16 v[52:55], v[140:143], v[120:123], v[52:55]
	v_mfma_f32_16x16x32_bf16 v[56:59], v[136:139], v[124:127], v[56:59]
	v_mfma_f32_16x16x32_bf16 v[60:63], v[140:143], v[124:127], v[60:63]
	s_waitcnt lgkmcnt(0)
	s_waitcnt vmcnt(0)
	s_barrier
	v_mfma_f32_16x16x32_bf16 v[32:35], v[176:179], v[144:147], v[32:35]
	s_add_u32 m0, s12, 0x6000
	ds_read_b128 v[96:99], v203 offset:0
	v_mfma_f32_16x16x32_bf16 v[36:39], v[180:183], v[144:147], v[36:39]
	global_load_lds_dwordx4 v192, s[2:3]
	s_add_u32 m0, s12, 0x6400
	ds_read_b128 v[100:103], v203 offset:2048
	v_mfma_f32_16x16x32_bf16 v[40:43], v[176:179], v[148:151], v[40:43]
	global_load_lds_dwordx4 v193, s[2:3]
	s_add_u32 m0, s12, 0x6800
	ds_read_b128 v[104:107], v203 offset:4096
	v_mfma_f32_16x16x32_bf16 v[44:47], v[180:183], v[148:151], v[44:47]
	global_load_lds_dwordx4 v194, s[2:3]
	s_add_u32 m0, s12, 0x6c00
	ds_read_b128 v[108:111], v203 offset:6144
	v_mfma_f32_16x16x32_bf16 v[48:51], v[176:179], v[152:155], v[48:51]
	global_load_lds_dwordx4 v195, s[2:3]
	s_add_u32 m0, s13, 0xa000
	ds_read_b128 v[128:131], v205 offset:16384
	v_mfma_f32_16x16x32_bf16 v[52:55], v[180:183], v[152:155], v[52:55]
	global_load_lds_dwordx4 v196, s[4:5]
	s_add_u32 m0, s13, 0xa400
	ds_read_b128 v[132:135], v205 offset:18432
	v_mfma_f32_16x16x32_bf16 v[56:59], v[176:179], v[156:159], v[56:59]
	global_load_lds_dwordx4 v197, s[4:5]
	ds_read_b128 v[112:115], v204 offset:0
	v_mfma_f32_16x16x32_bf16 v[60:63], v[180:183], v[156:159], v[60:63]
	s_add_u32 s2, s2, 0x80
	s_addc_u32 s3, s3, 0
	ds_read_b128 v[116:119], v204 offset:2048
	v_mfma_f32_16x16x32_bf16 v[32:35], v[184:187], v[160:163], v[32:35]
	s_add_u32 s4, s4, 0x80
	s_addc_u32 s5, s5, 0
	ds_read_b128 v[120:123], v204 offset:4096
	v_mfma_f32_16x16x32_bf16 v[36:39], v[188:191], v[160:163], v[36:39]
	ds_read_b128 v[124:127], v204 offset:6144
	v_mfma_f32_16x16x32_bf16 v[40:43], v[184:187], v[164:167], v[40:43]
	ds_read_b128 v[136:139], v206 offset:16384
	v_mfma_f32_16x16x32_bf16 v[44:47], v[188:191], v[164:167], v[44:47]
	ds_read_b128 v[140:143], v206 offset:18432
	v_mfma_f32_16x16x32_bf16 v[48:51], v[184:187], v[168:171], v[48:51]
	v_mfma_f32_16x16x32_bf16 v[52:55], v[188:191], v[168:171], v[52:55]
	v_mfma_f32_16x16x32_bf16 v[56:59], v[184:187], v[172:175], v[56:59]
	v_mfma_f32_16x16x32_bf16 v[60:63], v[188:191], v[172:175], v[60:63]
	s_waitcnt lgkmcnt(0)
	s_nop 7
	s_nop 1
	v_pk_fma_f32 v[0:1], v[32:33], v[64:65], v[0:1]
	v_pk_fma_f32 v[2:3], v[34:35], v[66:67], v[2:3]
	v_pk_fma_f32 v[4:5], v[36:37], v[68:69], v[4:5]
	v_pk_fma_f32 v[6:7], v[38:39], v[70:71], v[6:7]
	v_pk_fma_f32 v[8:9], v[40:41], v[72:73], v[8:9]
	v_pk_fma_f32 v[10:11], v[42:43], v[74:75], v[10:11]
	v_pk_fma_f32 v[12:13], v[44:45], v[76:77], v[12:13]
	v_pk_fma_f32 v[14:15], v[46:47], v[78:79], v[14:15]
	v_pk_fma_f32 v[16:17], v[48:49], v[80:81], v[16:17]
	v_pk_fma_f32 v[18:19], v[50:51], v[82:83], v[18:19]
	v_pk_fma_f32 v[20:21], v[52:53], v[84:85], v[20:21]
	v_pk_fma_f32 v[22:23], v[54:55], v[86:87], v[22:23]
	v_pk_fma_f32 v[24:25], v[56:57], v[88:89], v[24:25]
	v_pk_fma_f32 v[26:27], v[58:59], v[90:91], v[26:27]
	v_pk_fma_f32 v[28:29], v[60:61], v[92:93], v[28:29]
	v_pk_fma_f32 v[30:31], v[62:63], v[94:95], v[30:31]
	v_mov_b32_e32 v32, 0
	v_mov_b32_e32 v33, 0
	v_mov_b32_e32 v34, 0
	v_mov_b32_e32 v35, 0
	v_mov_b32_e32 v36, 0
	v_mov_b32_e32 v37, 0
	v_mov_b32_e32 v38, 0
	v_mov_b32_e32 v39, 0
	v_mov_b32_e32 v40, 0
	v_mov_b32_e32 v41, 0
	v_mov_b32_e32 v42, 0
	v_mov_b32_e32 v43, 0
	v_mov_b32_e32 v44, 0
	v_mov_b32_e32 v45, 0
	v_mov_b32_e32 v46, 0
	v_mov_b32_e32 v47, 0
	v_mov_b32_e32 v48, 0
	v_mov_b32_e32 v49, 0
	v_mov_b32_e32 v50, 0
	v_mov_b32_e32 v51, 0
	v_mov_b32_e32 v52, 0
	v_mov_b32_e32 v53, 0
	v_mov_b32_e32 v54, 0
	v_mov_b32_e32 v55, 0
	v_mov_b32_e32 v56, 0
	v_mov_b32_e32 v57, 0
	v_mov_b32_e32 v58, 0
	v_mov_b32_e32 v59, 0
	v_mov_b32_e32 v60, 0
	v_mov_b32_e32 v61, 0
	v_mov_b32_e32 v62, 0
	v_mov_b32_e32 v63, 0
	s_add_u32 s17, s17, 1
	s_branch .Lg4_nloop
.Lg4_last:
	s_waitcnt vmcnt(0)
	s_barrier
	v_mfma_f32_16x16x32_bf16 v[32:35], v[128:131], v[96:99], v[32:35]
	ds_read_b128 v[144:147], v203 offset:24576
	v_mfma_f32_16x16x32_bf16 v[36:39], v[132:135], v[96:99], v[36:39]
	ds_read_b128 v[148:151], v203 offset:26624
	v_mfma_f32_16x16x32_bf16 v[40:43], v[128:131], v[100:103], v[40:43]
	ds_read_b128 v[152:155], v203 offset:28672
	v_mfma_f32_16x16x32_bf16 v[44:47], v[132:135], v[100:103], v[44:47]
	ds_read_b128 v[156:159], v203 offset:30720
	v_mfma_f32_16x16x32_bf16 v[48:51], v[128:131], v[104:107], v[48:51]
	ds_read_b128 v[176:179], v205 offset:40960
	v_mfma_f32_16x16x32_bf16 v[52:55], v[132:135], v[104:107], v[52:55]
	ds_read_b128 v[180:183], v205 offset:43008
	v_mfma_f32_16x16x32_bf16 v[56:59], v[128:131], v[108:111], v[56:59]
	ds_read_b128 v[160:163], v204 offset:24576
	v_mfma_f32_16x16x32_bf16 v[60:63], v[132:135], v[108:111], v[60:63]
	ds_read_b128 v[164:167], v204 offset:26624
	v_mfma_f32_16x16x32_bf16 v[32:35], v[136:139], v[112:115], v[32:35]
	ds_read_b128 v[168:171], v204 offset:28672
	v_mfma_f32_16x16x32_bf16 v[36:39], v[140:143], v[112:115], v[36:39]
	ds_read_b128 v[172:175], v204 offset:30720
	v_mfma_f32_16x16x32_bf16 v[40:43], v[136:139], v[116:119], v[40:43]
	ds_read_b128 v[184:187], v206 offset:40960
	v_mfma_f32_16x16x32_bf16 v[44:47], v[140:143], v[116:119], v[44:47]
	ds_read_b128 v[188:191], v206 offset:43008
	v_mfma_f32_16x16x32_bf16 v[48:51], v[136:139], v[120:123], v[48:51]
	v_mfma_f32_16x16x32_bf16 v[52:55], v[140:143], v[120:123], v[52:55]
	v_mfma_f32_16x16x32_bf16 v[56:59], v[136:139], v[124:127], v[56:59]
	v_mfma_f32_16x16x32_bf16 v[60:63], v[140:143], v[124:127], v[60:63]
	s_waitcnt lgkmcnt(0)
	v_mfma_f32_16x16x32_bf16 v[32:35], v[176:179], v[144:147], v[32:35]
	v_mfma_f32_16x16x32_bf16 v[36:39], v[180:183], v[144:147], v[36:39]
	v_mfma_f32_16x16x32_bf16 v[40:43], v[176:179], v[148:151], v[40:43]
	v_mfma_f32_16x16x32_bf16 v[44:47], v[180:183], v[148:151], v[44:47]
	v_mfma_f32_16x16x32_bf16 v[48:51], v[176:179], v[152:155], v[48:51]
	v_mfma_f32_16x16x32_bf16 v[52:55], v[180:183], v[152:155], v[52:55]
	v_mfma_f32_16x16x32_bf16 v[56:59], v[176:179], v[156:159], v[56:59]
	v_mfma_f32_16x16x32_bf16 v[60:63], v[180:183], v[156:159], v[60:63]
	v_mfma_f32_16x16x32_bf16 v[32:35], v[184:187], v[160:163], v[32:35]
	v_mfma_f32_16x16x32_bf16 v[36:39], v[188:191], v[160:163], v[36:39]
	v_mfma_f32_16x16x32_bf16 v[40:43], v[184:187], v[164:167], v[40:43]
	v_mfma_f32_16x16x32_bf16 v[44:47], v[188:191], v[164:167], v[44:47]
	v_mfma_f32_16x16x32_bf16 v[48:51], v[184:187], v[168:171], v[48:51]
	v_mfma_f32_16x16x32_bf16 v[52:55], v[188:191], v[168:171], v[52:55]
	v_mfma_f32_16x16x32_bf16 v[56:59], v[184:187], v[172:175], v[56:59]
	v_mfma_f32_16x16x32_bf16 v[60:63], v[188:191], v[172:175], v[60:63]
	s_nop 7
	s_nop 1
	v_pk_fma_f32 v[0:1], v[32:33], v[64:65], v[0:1]
	v_pk_fma_f32 v[2:3], v[34:35], v[66:67], v[2:3]
	v_pk_fma_f32 v[4:5], v[36:37], v[68:69], v[4:5]
	v_pk_fma_f32 v[6:7], v[38:39], v[70:71], v[6:7]
	v_pk_fma_f32 v[8:9], v[40:41], v[72:73], v[8:9]
	v_pk_fma_f32 v[10:11], v[42:43], v[74:75], v[10:11]
	v_pk_fma_f32 v[12:13], v[44:45], v[76:77], v[12:13]
	v_pk_fma_f32 v[14:15], v[46:47], v[78:79], v[14:15]
	v_pk_fma_f32 v[16:17], v[48:49], v[80:81], v[16:17]
	v_pk_fma_f32 v[18:19], v[50:51], v[82:83], v[18:19]
	v_pk_fma_f32 v[20:21], v[52:53], v[84:85], v[20:21]
	v_pk_fma_f32 v[22:23], v[54:55], v[86:87], v[22:23]
	v_pk_fma_f32 v[24:25], v[56:57], v[88:89], v[24:25]
	v_pk_fma_f32 v[26:27], v[58:59], v[90:91], v[26:27]
	v_pk_fma_f32 v[28:29], v[60:61], v[92:93], v[28:29]
	v_pk_fma_f32 v[30:31], v[62:63], v[94:95], v[30:31]
	s_lshl_b32 s14, s20, 18
	s_lshl_b32 s15, s21, 7
	s_add_u32 s14, s14, s15
	s_add_u32 s2, s28, s14
	s_addc_u32 s3, s29, 0
	v_and_b32_e32 v96, 63, v216
	v_lshrrev_b32_e32 v97, 6, v216
	v_and_b32_e32 v98, 15, v96
	v_lshrrev_b32_e32 v96, 4, v96
	v_lshlrev_b32_e32 v96, 3, v96
	v_lshl_add_u32 v96, v98, 11, v96
	v_and_b32_e32 v98, 1, v97
	v_lshl_add_u32 v96, v98, 6, v96
	v_lshrrev_b32_e32 v97, 1, v97
	v_lshl_add_u32 v100, v97, 17, v96
	v_add_u32_e32 v101, 0x8000, v100
	v_add_u32_e32 v102, 0x10000, v100
	v_add_u32_e32 v103, 0x18000, v100
	v_bfe_u32 v200, v0, 16, 1
	v_bfe_u32 v207, v1, 16, 1
	v_bfe_u32 v208, v2, 16, 1
	v_bfe_u32 v209, v3, 16, 1
	v_add3_u32 v0, v0, v200, s69
	v_add3_u32 v1, v1, v207, s69
	v_add3_u32 v2, v2, v208, s69
	v_add3_u32 v3, v3, v209, s69
	v_lshrrev_b32_e32 v0, 16, v0
	v_lshrrev_b32_e32 v2, 16, v2
	v_and_or_b32 v104, v1, s30, v0
	v_and_or_b32 v105, v3, s30, v2
	global_store_dwordx2 v100, v[104:105], s[2:3]
	v_bfe_u32 v200, v4, 16, 1
	v_bfe_u32 v207, v5, 16, 1
	v_bfe_u32 v208, v6, 16, 1
	v_bfe_u32 v209, v7, 16, 1
	v_add3_u32 v4, v4, v200, s69
	v_add3_u32 v5, v5, v207, s69
	v_add3_u32 v6, v6, v208, s69
	v_add3_u32 v7, v7, v209, s69
	v_lshrrev_b32_e32 v4, 16, v4
	v_lshrrev_b32_e32 v6, 16, v6
	v_and_or_b32 v106, v5, s30, v4
	v_and_or_b32 v107, v7, s30, v6
	global_store_dwordx2 v100, v[106:107], s[2:3] offset:32
	v_bfe_u32 v200, v8, 16, 1
	v_bfe_u32 v207, v9, 16, 1
	v_bfe_u32 v208, v10, 16, 1
	v_bfe_u32 v209, v11, 16, 1
	v_add3_u32 v8, v8, v200, s69
	v_add3_u32 v9, v9, v207, s69
	v_add3_u32 v10, v10, v208, s69
	v_add3_u32 v11, v11, v209, s69
	v_lshrrev_b32_e32 v8, 16, v8
	v_lshrrev_b32_e32 v10, 16, v10
	v_and_or_b32 v108, v9, s30, v8
	v_and_or_b32 v109, v11, s30, v10
	global_store_dwordx2 v101, v[108:109], s[2:3]
	v_bfe_u32 v200, v12, 16, 1
	v_bfe_u32 v207, v13, 16, 1
	v_bfe_u32 v208, v14, 16, 1
	v_bfe_u32 v209, v15, 16, 1
	v_add3_u32 v12, v12, v200, s69
	v_add3_u32 v13, v13, v207, s69
	v_add3_u32 v14, v14, v208, s69
	v_add3_u32 v15, v15, v209, s69
	v_lshrrev_b32_e32 v12, 16, v12
	v_lshrrev_b32_e32 v14, 16, v14
	v_and_or_b32 v110, v13, s30, v12
	v_and_or_b32 v111, v15, s30, v14
	global_store_dwordx2 v101, v[110:111], s[2:3] offset:32
	v_bfe_u32 v200, v16, 16, 1
	v_bfe_u32 v207, v17, 16, 1
	v_bfe_u32 v208, v18, 16, 1
	v_bfe_u32 v209, v19, 16, 1
	v_add3_u32 v16, v16, v200, s69
	v_add3_u32 v17, v17, v207, s69
	v_add3_u32 v18, v18, v208, s69
	v_add3_u32 v19, v19, v209, s69
	v_lshrrev_b32_e32 v16, 16, v16
	v_lshrrev_b32_e32 v18, 16, v18
	v_and_or_b32 v112, v17, s30, v16
	v_and_or_b32 v113, v19, s30, v18
	global_store_dwordx2 v102, v[112:113], s[2:3]
	v_bfe_u32 v200, v20, 16, 1
	v_bfe_u32 v207, v21, 16, 1
	v_bfe_u32 v208, v22, 16, 1
	v_bfe_u32 v209, v23, 16, 1
	v_add3_u32 v20, v20, v200, s69
	v_add3_u32 v21, v21, v207, s69
	v_add3_u32 v22, v22, v208, s69
	v_add3_u32 v23, v23, v209, s69
	v_lshrrev_b32_e32 v20, 16, v20
	v_lshrrev_b32_e32 v22, 16, v22
	v_and_or_b32 v114, v21, s30, v20
	v_and_or_b32 v115, v23, s30, v22
	global_store_dwordx2 v102, v[114:115], s[2:3] offset:32
	v_bfe_u32 v200, v24, 16, 1
	v_bfe_u32 v207, v25, 16, 1
	v_bfe_u32 v208, v26, 16, 1
	v_bfe_u32 v209, v27, 16, 1
	v_add3_u32 v24, v24, v200, s69
	v_add3_u32 v25, v25, v207, s69
	v_add3_u32 v26, v26, v208, s69
	v_add3_u32 v27, v27, v209, s69
	v_lshrrev_b32_e32 v24, 16, v24
	v_lshrrev_b32_e32 v26, 16, v26
	v_and_or_b32 v116, v25, s30, v24
	v_and_or_b32 v117, v27, s30, v26
	global_store_dwordx2 v103, v[116:117], s[2:3]
	v_bfe_u32 v200, v28, 16, 1
	v_bfe_u32 v207, v29, 16, 1
	v_bfe_u32 v208, v30, 16, 1
	v_bfe_u32 v209, v31, 16, 1
	v_add3_u32 v28, v28, v200, s69
	v_add3_u32 v29, v29, v207, s69
	v_add3_u32 v30, v30, v208, s69
	v_add3_u32 v31, v31, v209, s69
	v_lshrrev_b32_e32 v28, 16, v28
	v_lshrrev_b32_e32 v30, 16, v30
	v_and_or_b32 v118, v29, s30, v28
	v_and_or_b32 v119, v31, s30, v30
	global_store_dwordx2 v103, v[118:119], s[2:3] offset:32
	s_branch .LBB0_871
